# DA loops: O-rescale multiplies and alpha exps interleaved into the exp block
# baseline (speedup 1.0000x reference)
; DI void attn_pass_da(const bfr* __restrict__ P, int b, int tq_wave, int qcol, int kcol, int vcol, int key0, int nkt, char* smem, f32x16 (&o0)[2], f32x16 (&o1)[2]) {
;     ...
;   for (int kt = 0; kt < nkt; ++kt) {
;     bfr* sK = sbase + (kt & 1) * 9216;
;     bfr* sV = sK + 64 * 72;
;     { int c = gt, row = c >> 3, kc = c & 7; *(u32x4*)(sK + row * KP + kc * 8) = kreg[0]; }
;     for (int i = 0; i < 1; ++i) {
;       int c = gt, row = c >> 3, kc = c & 7;
;       unsigned wds[4] = {vreg[i].x, vreg[i].y, vreg[i].z, vreg[i].w};
; #pragma unroll
;       for (int e = 0; e < 4; ++e) {
;         sV[(kc * 8 + 2 * e) * 72 + (row ^ (kc << 3))] = (bfr)(wds[e] & 0xffffu);
;         sV[(kc * 8 + 2 * e + 1) * 72 + (row ^ (kc << 3))] = (bfr)(wds[e] >> 16);
;       }
;     }
;     __syncthreads();
;     if (kt + 1 < nkt) {
;       const bfr* Pn = Pb + (size_t)(kt + 1) * 64 * PW;
;       { int c = gt, row = c >> 3, kc = c & 7; kreg[0] = *(const u32x4*)(Pn + (size_t)row * PW + kcol + kc * 8); vreg[0] = *(const u32x4*)(Pn + (size_t)row * PW + vcol + kc * 8); }
;     }
;     f32x16 s0[2], s1[2];
; #pragma unroll
;     for (int t2 = 0; t2 < 2; ++t2) {
; #pragma unroll
;       for (int i = 0; i < 16; ++i) { s0[t2][i] = 0.f; s1[t2][i] = 0.f; }
; #pragma unroll
;       for (int ks = 0; ks < 2; ++ks) {
;         bf16x8 a0 = *(const bf16x8*)(sK + (t2 * 32 + r) * KP + ks * 16 + h * 8);
;         bf16x8 a1 = *(const bf16x8*)(sK + (t2 * 32 + r) * KP + 32 + ks * 16 + h * 8);
;         s0[t2] = MFMA32(a0, qf[ks], s0[t2]);
;         s1[t2] = MFMA32(a1, qf[2 + ks], s1[t2]);
;       }
;     }
;     float mx0 = s0[0][0], mx1 = s1[0][0];
; #pragma unroll
;     for (int i = 0; i < 16; ++i) { mx0 = fmaxf(mx0, fmaxf(s0[0][i], s0[1][i])); mx1 = fmaxf(mx1, fmaxf(s1[0][i], s1[1][i])); }
;     mx0 = fmaxf(mx0, __shfl_xor(mx0, 32)); mx1 = fmaxf(mx1, __shfl_xor(mx1, 32));
;     const float mn0 = fmaxf(m0, mx0), mn1 = fmaxf(m1, mx1);
;     const float al0 = __builtin_amdgcn_exp2f(m0 - mn0), al1 = __builtin_amdgcn_exp2f(m1 - mn1);
;     m0 = mn0; m1 = mn1;
;     float ps0 = 0.f, ps1 = 0.f;
; #pragma unroll
;     for (int i = 0; i < 16; ++i) {
;       s0[0][i] = __builtin_amdgcn_exp2f(s0[0][i] - mn0); ps0 += s0[0][i];
;       s0[1][i] = __builtin_amdgcn_exp2f(s0[1][i] - mn0); ps0 += s0[1][i];
;       s1[0][i] = __builtin_amdgcn_exp2f(s1[0][i] - mn1); ps1 += s1[0][i];
.LBB0_408:
	s_bitcmp1_b32 s14, 0
	s_cselect_b32 s15, 0x4800, 0
	s_add_i32 s15, s15, 0
	v_add3_u32 v64, s15, v206, v152
	v_add_u32_e32 v194, s15, v205
	s_waitcnt vmcnt(1)
	ds_write_b128 v64, v[148:151]
	v_add3_u32 v64, s15, v207, v208
	v_add3_u32 v65, s15, v208, v207
	v_add_u32_e32 v100, v194, v204
	s_waitcnt vmcnt(0)
	ds_write_b16 v64, v144 offset:9216
	ds_write_b16_d16_hi v65, v144 offset:9360
	ds_write_b16 v64, v145 offset:9504
	ds_write_b16_d16_hi v65, v145 offset:9648
	ds_write_b16 v64, v146 offset:9792
	ds_write_b16_d16_hi v65, v146 offset:9936
	ds_write_b16 v64, v147 offset:10080
	ds_write_b16_d16_hi v65, v147 offset:10224
	s_waitcnt lgkmcnt(0)
	s_barrier
	global_load_dwordx4 v[148:151], v[158:159], off
	global_load_dwordx4 v[144:147], v[158:159], off offset:512
	ds_read_b128 v[64:67], v100 offset:64
	ds_read_b128 v[68:71], v100
	ds_read_b128 v[96:99], v100 offset:32
	ds_read_b128 v[100:103], v100 offset:96
	s_waitcnt lgkmcnt(2)
	v_mfma_f32_32x32x16_bf16 v[80:95], v[68:71], v[140:143], 0
	v_add_u32_e32 v195, s15, v211
	v_add_u32_e32 v192, v195, v204
	v_mov_b32_e32 v160, v209
	v_mov_b32_e32 v161, v210
	s_add_i32 s14, s14, 1
	v_lshl_add_u64 v[158:159], v[158:159], 0, s[16:17]
	s_cmp_lg_u32 s14, 3
	v_mfma_f32_32x32x16_bf16 v[64:79], v[64:67], v[136:139], 0
	s_waitcnt lgkmcnt(1)
	v_mfma_f32_32x32x16_bf16 v[80:95], v[96:99], v[132:135], v[80:95]
	s_waitcnt lgkmcnt(0)
	v_mfma_f32_32x32x16_bf16 v[64:79], v[100:103], v[128:131], v[64:79]
	ds_read_b128 v[96:99], v192 offset:64
	ds_read_b128 v[100:103], v192
	ds_read_b128 v[212:215], v192 offset:32
	ds_read_b128 v[216:219], v192 offset:96
	s_nop 5
	v_max3_f32 v209, v80, v81, v82
	v_max3_f32 v209, v209, v83, v84
	v_max3_f32 v193, v64, v65, v66
	s_waitcnt lgkmcnt(2)
	v_mfma_f32_32x32x16_bf16 v[112:127], v[100:103], v[140:143], 0
	v_mfma_f32_32x32x16_bf16 v[96:111], v[96:99], v[136:139], 0
	s_waitcnt lgkmcnt(1)
	v_mfma_f32_32x32x16_bf16 v[112:127], v[212:215], v[132:135], v[112:127]
	v_max3_f32 v193, v193, v67, v68
	v_max3_f32 v209, v209, v85, v86
	s_waitcnt lgkmcnt(0)
	v_mfma_f32_32x32x16_bf16 v[96:111], v[216:219], v[128:131], v[96:111]
	v_max3_f32 v193, v193, v69, v70
	v_max3_f32 v209, v209, v87, v88
	v_max3_f32 v193, v193, v71, v72
	v_max3_f32 v209, v209, v89, v90
	v_max3_f32 v193, v193, v73, v74
	v_max3_f32 v209, v209, v91, v92
	v_max3_f32 v193, v193, v75, v76
	v_max3_f32 v209, v209, v93, v94
	v_max3_f32 v193, v193, v77, v78
	v_max3_f32 v209, v209, v95, v112
	v_max3_f32 v209, v209, v113, v114
	v_max3_f32 v209, v209, v115, v116
	v_max3_f32 v209, v209, v117, v118
	v_max3_f32 v209, v209, v119, v120
	v_max3_f32 v209, v209, v121, v122
	v_max3_f32 v209, v209, v123, v124
	v_max3_f32 v209, v209, v125, v126
	v_max_f32_e32 v192, v209, v127
	v_max3_f32 v193, v193, v79, v96
	v_max3_f32 v193, v193, v97, v98
	v_max3_f32 v193, v193, v99, v100
	v_max3_f32 v193, v193, v101, v102
	v_max3_f32 v193, v193, v103, v104
	v_max3_f32 v193, v193, v105, v106
	v_max3_f32 v193, v193, v107, v108
	v_max3_f32 v193, v193, v109, v110
	v_max_f32_e32 v193, v193, v111
	ds_bpermute_b32 v210, v166, v193
	ds_bpermute_b32 v209, v166, v192
	s_waitcnt lgkmcnt(1)
	v_max3_f32 v210, v161, v193, v210
	s_waitcnt lgkmcnt(0)
	v_max3_f32 v209, v160, v192, v209
	v_sub_f32_e32 v161, v161, v210
	v_sub_f32_e32 v160, v160, v209
	v_exp_f32_e32 v161, v161
	v_exp_f32_e32 v160, v160
	v_pk_add_f32 v[64:65], v[64:65], v[210:211] op_sel_hi:[1,0] neg_lo:[0,1] neg_hi:[0,1]
	v_pk_add_f32 v[80:81], v[80:81], v[208:209] op_sel:[0,1] op_sel_hi:[1,1] neg_lo:[0,1] neg_hi:[0,1]
	v_exp_f32_e32 v193, v64
	v_pk_add_f32 v[96:97], v[96:97], v[210:211] op_sel_hi:[1,0] neg_lo:[0,1] neg_hi:[0,1]
	v_exp_f32_e32 v192, v80
	v_pk_mul_f32 v[62:63], v[62:63], v[160:161] op_sel_hi:[1,0]
	v_pk_add_f32 v[112:113], v[112:113], v[208:209] op_sel:[0,1] op_sel_hi:[1,1] neg_lo:[0,1] neg_hi:[0,1]
	v_exp_f32_e32 v213, v96
	v_exp_f32_e32 v212, v112
	v_pk_mul_f32 v[60:61], v[60:61], v[160:161] op_sel_hi:[1,0]
	v_exp_f32_e32 v80, v81
	v_exp_f32_e32 v96, v113
	v_pk_mul_f32 v[58:59], v[58:59], v[160:161] op_sel_hi:[1,0]
	v_exp_f32_e32 v81, v65
	v_exp_f32_e32 v97, v97
	v_pk_mul_f32 v[56:57], v[56:57], v[160:161] op_sel_hi:[1,0]
	v_pk_add_f32 v[82:83], v[82:83], v[208:209] op_sel:[0,1] op_sel_hi:[1,1] neg_lo:[0,1] neg_hi:[0,1]
	v_exp_f32_e32 v112, v82
	v_pk_add_f32 v[114:115], v[114:115], v[208:209] op_sel:[0,1] op_sel_hi:[1,1] neg_lo:[0,1] neg_hi:[0,1]
	v_exp_f32_e32 v214, v114
	v_pk_mul_f32 v[54:55], v[54:55], v[160:161] op_sel_hi:[1,0]
	v_pk_add_f32 v[66:67], v[66:67], v[210:211] op_sel_hi:[1,0] neg_lo:[0,1] neg_hi:[0,1]
	v_exp_f32_e32 v113, v66
	v_pk_add_f32 v[98:99], v[98:99], v[210:211] op_sel_hi:[1,0] neg_lo:[0,1] neg_hi:[0,1]
	v_exp_f32_e32 v215, v98
	v_pk_mul_f32 v[52:53], v[52:53], v[160:161] op_sel_hi:[1,0]
	v_exp_f32_e32 v82, v83
	v_exp_f32_e32 v98, v115
	v_pk_mul_f32 v[50:51], v[50:51], v[160:161] op_sel_hi:[1,0]
	v_exp_f32_e32 v83, v67
	v_exp_f32_e32 v99, v99
	v_pk_mul_f32 v[48:49], v[48:49], v[160:161] op_sel_hi:[1,0]
	v_pk_add_f32 v[84:85], v[84:85], v[208:209] op_sel:[0,1] op_sel_hi:[1,1] neg_lo:[0,1] neg_hi:[0,1]
	v_exp_f32_e32 v114, v84
	v_pk_add_f32 v[116:117], v[116:117], v[208:209] op_sel:[0,1] op_sel_hi:[1,1] neg_lo:[0,1] neg_hi:[0,1]
	v_exp_f32_e32 v216, v116
	v_pk_mul_f32 v[30:31], v[30:31], v[160:161] op_sel_hi:[1,0]
	v_pk_add_f32 v[68:69], v[68:69], v[210:211] op_sel_hi:[1,0] neg_lo:[0,1] neg_hi:[0,1]
	v_exp_f32_e32 v115, v68
	v_pk_add_f32 v[100:101], v[100:101], v[210:211] op_sel_hi:[1,0] neg_lo:[0,1] neg_hi:[0,1]
	v_exp_f32_e32 v217, v100
	v_pk_mul_f32 v[28:29], v[28:29], v[160:161] op_sel_hi:[1,0]
	v_exp_f32_e32 v84, v85
	v_exp_f32_e32 v100, v117
; DI void attn_pass_da(const bfr* __restrict__ P, int b, int tq_wave, int qcol, int kcol, int vcol, int key0, int nkt, char* smem, f32x16 (&o0)[2], f32x16 (&o1)[2]) {
;     ...
;     const float al0 = __builtin_amdgcn_exp2f(m0 - mn0), al1 = __builtin_amdgcn_exp2f(m1 - mn1);
;     m0 = mn0; m1 = mn1;
;     float ps0 = 0.f, ps1 = 0.f;
; #pragma unroll
;     for (int i = 0; i < 16; ++i) {
;       s0[0][i] = __builtin_amdgcn_exp2f(s0[0][i] - mn0); ps0 += s0[0][i];
;       s0[1][i] = __builtin_amdgcn_exp2f(s0[1][i] - mn0); ps0 += s0[1][i];
;       s1[0][i] = __builtin_amdgcn_exp2f(s1[0][i] - mn1); ps1 += s1[0][i];
;       s1[1][i] = __builtin_amdgcn_exp2f(s1[1][i] - mn1); ps1 += s1[1][i];
;     }
;     l0 = l0 * al0 + ps0; l1 = l1 * al1 + ps1;
; #pragma unroll
;     for (int i = 0; i < 16; ++i) { acc0[0][i] *= al0; acc0[1][i] *= al0; acc1[0][i] *= al1; acc1[1][i] *= al1; }
	v_pk_mul_f32 v[26:27], v[26:27], v[160:161] op_sel_hi:[1,0]
	v_exp_f32_e32 v85, v69
	v_exp_f32_e32 v101, v101
	v_pk_mul_f32 v[24:25], v[24:25], v[160:161] op_sel_hi:[1,0]
	v_pk_add_f32 v[86:87], v[86:87], v[208:209] op_sel:[0,1] op_sel_hi:[1,1] neg_lo:[0,1] neg_hi:[0,1]
	v_exp_f32_e32 v116, v86
	v_pk_add_f32 v[118:119], v[118:119], v[208:209] op_sel:[0,1] op_sel_hi:[1,1] neg_lo:[0,1] neg_hi:[0,1]
	v_exp_f32_e32 v218, v118
	v_pk_mul_f32 v[22:23], v[22:23], v[160:161] op_sel_hi:[1,0]
	v_pk_add_f32 v[70:71], v[70:71], v[210:211] op_sel_hi:[1,0] neg_lo:[0,1] neg_hi:[0,1]
	v_exp_f32_e32 v117, v70
	v_pk_add_f32 v[102:103], v[102:103], v[210:211] op_sel_hi:[1,0] neg_lo:[0,1] neg_hi:[0,1]
	v_exp_f32_e32 v219, v102
	v_pk_mul_f32 v[20:21], v[20:21], v[160:161] op_sel_hi:[1,0]
	v_exp_f32_e32 v70, v87
	v_exp_f32_e32 v86, v119
	v_pk_mul_f32 v[46:47], v[46:47], v[160:161] op_sel:[0,1] op_sel_hi:[1,1]
	v_exp_f32_e32 v71, v71
	v_exp_f32_e32 v87, v103
	v_pk_mul_f32 v[44:45], v[44:45], v[160:161] op_sel:[0,1] op_sel_hi:[1,1]
	v_pk_add_f32 v[88:89], v[88:89], v[208:209] op_sel:[0,1] op_sel_hi:[1,1] neg_lo:[0,1] neg_hi:[0,1]
	v_exp_f32_e32 v102, v88
	v_pk_add_f32 v[120:121], v[120:121], v[208:209] op_sel:[0,1] op_sel_hi:[1,1] neg_lo:[0,1] neg_hi:[0,1]
	v_exp_f32_e32 v118, v120
	v_pk_mul_f32 v[42:43], v[42:43], v[160:161] op_sel:[0,1] op_sel_hi:[1,1]
	v_pk_add_f32 v[72:73], v[72:73], v[210:211] op_sel_hi:[1,0] neg_lo:[0,1] neg_hi:[0,1]
	v_exp_f32_e32 v103, v72
	v_pk_add_f32 v[104:105], v[104:105], v[210:211] op_sel_hi:[1,0] neg_lo:[0,1] neg_hi:[0,1]
	v_exp_f32_e32 v119, v104
	v_pk_mul_f32 v[40:41], v[40:41], v[160:161] op_sel:[0,1] op_sel_hi:[1,1]
	v_exp_f32_e32 v88, v89
	v_exp_f32_e32 v104, v121
	v_pk_mul_f32 v[38:39], v[38:39], v[160:161] op_sel:[0,1] op_sel_hi:[1,1]
	v_exp_f32_e32 v89, v73
	v_exp_f32_e32 v105, v105
	v_pk_mul_f32 v[36:37], v[36:37], v[160:161] op_sel:[0,1] op_sel_hi:[1,1]
	v_pk_add_f32 v[90:91], v[90:91], v[208:209] op_sel:[0,1] op_sel_hi:[1,1] neg_lo:[0,1] neg_hi:[0,1]
	v_exp_f32_e32 v120, v90
	v_pk_add_f32 v[122:123], v[122:123], v[208:209] op_sel:[0,1] op_sel_hi:[1,1] neg_lo:[0,1] neg_hi:[0,1]
	v_exp_f32_e32 v220, v122
	v_pk_mul_f32 v[34:35], v[34:35], v[160:161] op_sel:[0,1] op_sel_hi:[1,1]
	v_pk_add_f32 v[74:75], v[74:75], v[210:211] op_sel_hi:[1,0] neg_lo:[0,1] neg_hi:[0,1]
	v_exp_f32_e32 v121, v74
	v_pk_add_f32 v[106:107], v[106:107], v[210:211] op_sel_hi:[1,0] neg_lo:[0,1] neg_hi:[0,1]
	v_exp_f32_e32 v221, v106
	v_pk_mul_f32 v[32:33], v[32:33], v[160:161] op_sel:[0,1] op_sel_hi:[1,1]
	v_exp_f32_e32 v90, v91
	v_exp_f32_e32 v106, v123
	v_pk_mul_f32 v[14:15], v[14:15], v[160:161] op_sel:[0,1] op_sel_hi:[1,1]
	v_exp_f32_e32 v91, v75
	v_exp_f32_e32 v107, v107
	v_pk_mul_f32 v[12:13], v[12:13], v[160:161] op_sel:[0,1] op_sel_hi:[1,1]
	v_pk_add_f32 v[92:93], v[92:93], v[208:209] op_sel:[0,1] op_sel_hi:[1,1] neg_lo:[0,1] neg_hi:[0,1]
	v_exp_f32_e32 v122, v92
	v_pk_add_f32 v[124:125], v[124:125], v[208:209] op_sel:[0,1] op_sel_hi:[1,1] neg_lo:[0,1] neg_hi:[0,1]
	v_exp_f32_e32 v222, v124
	v_pk_mul_f32 v[10:11], v[10:11], v[160:161] op_sel:[0,1] op_sel_hi:[1,1]
	v_pk_add_f32 v[76:77], v[76:77], v[210:211] op_sel_hi:[1,0] neg_lo:[0,1] neg_hi:[0,1]
	v_exp_f32_e32 v123, v76
	v_pk_add_f32 v[108:109], v[108:109], v[210:211] op_sel_hi:[1,0] neg_lo:[0,1] neg_hi:[0,1]
	v_exp_f32_e32 v223, v108
	v_pk_mul_f32 v[8:9], v[8:9], v[160:161] op_sel:[0,1] op_sel_hi:[1,1]
	v_exp_f32_e32 v92, v93
	v_exp_f32_e32 v108, v125
	v_pk_mul_f32 v[6:7], v[6:7], v[160:161] op_sel:[0,1] op_sel_hi:[1,1]
	v_exp_f32_e32 v93, v77
	v_exp_f32_e32 v109, v109
	v_pk_mul_f32 v[4:5], v[4:5], v[160:161] op_sel:[0,1] op_sel_hi:[1,1]
	v_pk_add_f32 v[94:95], v[94:95], v[208:209] op_sel:[0,1] op_sel_hi:[1,1] neg_lo:[0,1] neg_hi:[0,1]
	v_exp_f32_e32 v124, v94
	v_pk_add_f32 v[126:127], v[126:127], v[208:209] op_sel:[0,1] op_sel_hi:[1,1] neg_lo:[0,1] neg_hi:[0,1]
	v_exp_f32_e32 v224, v126
	v_pk_mul_f32 v[2:3], v[2:3], v[160:161] op_sel:[0,1] op_sel_hi:[1,1]
	v_pk_add_f32 v[78:79], v[78:79], v[210:211] op_sel_hi:[1,0] neg_lo:[0,1] neg_hi:[0,1]
	v_exp_f32_e32 v125, v78
	v_pk_add_f32 v[110:111], v[110:111], v[210:211] op_sel_hi:[1,0] neg_lo:[0,1] neg_hi:[0,1]
	v_exp_f32_e32 v225, v110
	v_pk_mul_f32 v[0:1], v[0:1], v[160:161] op_sel:[0,1] op_sel_hi:[1,1]
	v_exp_f32_e32 v94, v95
	v_exp_f32_e32 v110, v127
	v_pk_mul_f32 v[18:19], v[18:19], v[160:161] op_sel_hi:[1,0]
	v_exp_f32_e32 v95, v79
	v_exp_f32_e32 v111, v111
	v_pk_mul_f32 v[16:17], v[16:17], v[160:161] op_sel_hi:[1,0]
	v_pk_add_f32 v[64:65], v[192:193], 0 op_sel_hi:[1,0]
	v_pk_add_f32 v[64:65], v[212:213], v[64:65]
	v_pk_add_f32 v[64:65], v[80:81], v[64:65]
	v_lshl_add_u32 v74, v180, 1, v194
	v_pk_add_f32 v[64:65], v[96:97], v[64:65]
	v_lshl_add_u32 v76, v179, 1, v195
	v_pk_add_f32 v[64:65], v[112:113], v[64:65]
	v_lshl_add_u32 v78, v178, 1, v195
	v_pk_add_f32 v[64:65], v[214:215], v[64:65]
	v_pk_add_f32 v[64:65], v[82:83], v[64:65]
	v_pk_add_f32 v[64:65], v[98:99], v[64:65]
	v_pk_add_f32 v[64:65], v[114:115], v[64:65]
	v_pk_add_f32 v[64:65], v[216:217], v[64:65]
	v_pk_add_f32 v[64:65], v[84:85], v[64:65]
	v_pk_add_f32 v[64:65], v[100:101], v[64:65]
	v_pk_add_f32 v[64:65], v[116:117], v[64:65]
	v_pk_add_f32 v[64:65], v[218:219], v[64:65]
	v_pk_add_f32 v[64:65], v[70:71], v[64:65]
	v_pk_add_f32 v[64:65], v[86:87], v[64:65]
	v_pk_add_f32 v[64:65], v[102:103], v[64:65]
	v_pk_add_f32 v[64:65], v[118:119], v[64:65]
	v_pk_add_f32 v[64:65], v[88:89], v[64:65]
	v_pk_add_f32 v[64:65], v[104:105], v[64:65]
	v_pk_add_f32 v[64:65], v[120:121], v[64:65]
	v_pk_add_f32 v[126:127], v[220:221], v[64:65]
	v_cvt_pk_bf16_f32 v64, v192, v80
	v_cvt_pk_bf16_f32 v65, v112, v82
	v_lshl_add_u32 v112, v181, 1, v194
	v_cvt_pk_bf16_f32 v66, v114, v84
	v_cvt_pk_bf16_f32 v67, v116, v70
	v_cvt_pk_bf16_f32 v68, v193, v81
	v_cvt_pk_bf16_f32 v69, v113, v83
	v_cvt_pk_bf16_f32 v70, v115, v85
	v_cvt_pk_bf16_f32 v71, v117, v71
	ds_read_b64 v[72:73], v112 offset:9216
	ds_read_b64 v[74:75], v74 offset:9216
	ds_read_b64 v[76:77], v76 offset:9216
	ds_read_b64 v[78:79], v78 offset:9216
	v_pk_add_f32 v[82:83], v[90:91], v[126:127]
	s_waitcnt lgkmcnt(2)
; DI void attn_pass_da(const bfr* __restrict__ P, int b, int tq_wave, int qcol, int kcol, int vcol, int key0, int nkt, char* smem, f32x16 (&o0)[2], f32x16 (&o1)[2]) {
;     ...
;     bfr* sK = sbase + (kt & 1) * 9216;
;     bfr* sV = sK + 64 * 72;
;     { int c = gt, row = c >> 3, kc = c & 7; *(u32x4*)(sK + row * KP + kc * 8) = kreg[0]; }
;     for (int i = 0; i < 1; ++i) {
;       int c = gt, row = c >> 3, kc = c & 7;
;       unsigned wds[4] = {vreg[i].x, vreg[i].y, vreg[i].z, vreg[i].w};
; #pragma unroll
;       for (int e = 0; e < 4; ++e) {
;         sV[(kc * 8 + 2 * e) * 72 + (row ^ (kc << 3))] = (bfr)(wds[e] & 0xffffu);
;         sV[(kc * 8 + 2 * e + 1) * 72 + (row ^ (kc << 3))] = (bfr)(wds[e] >> 16);
;       }
;     }
;     __syncthreads();
;     if (kt + 1 < nkt) {
;       const bfr* Pn = Pb + (size_t)(kt + 1) * 64 * PW;
;       { int c = gt, row = c >> 3, kc = c & 7; kreg[0] = *(const u32x4*)(Pn + (size_t)row * PW + kcol + kc * 8); vreg[0] = *(const u32x4*)(Pn + (size_t)row * PW + vcol + kc * 8); }
;     }
;     f32x16 s0[2], s1[2];
; #pragma unroll
;     for (int t2 = 0; t2 < 2; ++t2) {
; #pragma unroll
;     ...
;     for (int t2 = 0; t2 < 2; ++t2)
; #pragma unroll
;       for (int j = 0; j < 2; ++j) {
;         u32x4 pk0, pk1;
;         pk0.x = pack2(s0[t2][8 * j + 0], s0[t2][8 * j + 1]); pk0.y = pack2(s0[t2][8 * j + 2], s0[t2][8 * j + 3]);
;         pk0.z = pack2(s0[t2][8 * j + 4], s0[t2][8 * j + 5]); pk0.w = pack2(s0[t2][8 * j + 6], s0[t2][8 * j + 7]);
;         pk1.x = pack2(s1[t2][8 * j + 0], s1[t2][8 * j + 1]); pk1.y = pack2(s1[t2][8 * j + 2], s1[t2][8 * j + 3]);
;         pk1.z = pack2(s1[t2][8 * j + 4], s1[t2][8 * j + 5]); pk1.w = pack2(s1[t2][8 * j + 6], s1[t2][8 * j + 7]);
;         const bf16x8 pf0 = __builtin_bit_cast(bf16x8, pk0), pf1 = __builtin_bit_cast(bf16x8, pk1);
; #pragma unroll
;         for (int dt = 0; dt < 2; ++dt) {
;           const int vsw = (((dt * 32 + r) >> 3) & 7) << 3;
;           const bfr* vrow = sV + (dt * 32 + r) * 72;
;           s16x4 lo = *(const s16x4*)(vrow + ((t2 * 32 + 16 * j + 4 * h) ^ vsw));
;           s16x4 hi = *(const s16x4*)(vrow + ((t2 * 32 + 16 * j + 4 * h + 8) ^ vsw));
;           bf16x8 vf = __builtin_shufflevector(lo, hi, 0, 1, 2, 3, 4, 5, 6, 7);
;           acc0[dt] = MFMA32(vf, pf0, acc0[dt]);
;           acc1[dt] = MFMA32(vf, pf1, acc1[dt]);
;         }
;       }
	v_mfma_f32_32x32x16_bf16 v[48:63], v[72:75], v[64:67], v[48:63]
	v_add_f32_e64 v82, v106, v82
	v_add_f32_e64 v83, v107, v83
	v_cvt_pk_bf16_f32 v80, v102, v88
	v_lshl_add_u32 v88, v177, 1, v194
	v_add_f32_e64 v82, v122, v82
	v_add_f32_e64 v83, v123, v83
	v_pk_add_f32 v[82:83], v[222:223], v[82:83]
	v_pk_add_f32 v[82:83], v[92:93], v[82:83]
	v_mfma_f32_32x32x16_bf16 v[32:47], v[72:75], v[68:71], v[32:47]
	v_add_f32_e64 v82, v108, v82
	v_add_f32_e64 v83, v109, v83
	v_cvt_pk_bf16_f32 v81, v120, v90
	v_lshl_add_u32 v102, v176, 1, v194
	v_add_f32_e64 v82, v124, v82
	v_add_f32_e64 v83, v125, v83
	v_lshl_add_u32 v113, v175, 1, v195
	v_pk_add_f32 v[82:83], v[224:225], v[82:83]
	v_lshl_add_u32 v114, v174, 1, v195
	v_pk_add_f32 v[82:83], v[94:95], v[82:83]
	s_waitcnt lgkmcnt(0)
	v_mfma_f32_32x32x16_bf16 v[16:31], v[76:79], v[64:67], v[16:31]
	v_add_f32_e64 v84, v110, v82
	v_add_f32_e64 v85, v111, v83
	v_cvt_pk_bf16_f32 v82, v122, v92
	v_cvt_pk_bf16_f32 v83, v124, v94
	v_cvt_pk_bf16_f32 v64, v103, v89
	v_cvt_pk_bf16_f32 v65, v121, v91
	v_cvt_pk_bf16_f32 v66, v123, v93
	v_cvt_pk_bf16_f32 v67, v125, v95
	v_mfma_f32_32x32x16_bf16 v[0:15], v[76:79], v[68:71], v[0:15]
	ds_read_b64 v[68:69], v88 offset:9216
	ds_read_b64 v[70:71], v102 offset:9216
	v_lshl_add_u32 v115, v173, 1, v194
	v_lshl_add_u32 v116, v172, 1, v195
	v_lshl_add_u32 v117, v171, 1, v195
	v_lshl_add_u32 v120, v169, 1, v194
	v_lshl_add_u32 v192, v170, 1, v194
	v_lshl_add_u32 v193, v168, 1, v195
	s_waitcnt lgkmcnt(0)
	v_mfma_f32_32x32x16_bf16 v[48:63], v[68:71], v[80:83], v[48:63]
	v_lshl_add_u32 v194, v167, 1, v195
	v_fma_f32 v156, v156, v160, v84
	v_fma_f32 v157, v157, v161, v85
	v_mfma_f32_32x32x16_bf16 v[32:47], v[68:71], v[64:67], v[32:47]
	ds_read_b64 v[68:69], v113 offset:9216
	ds_read_b64 v[70:71], v114 offset:9216
	s_waitcnt lgkmcnt(0)
	v_mfma_f32_32x32x16_bf16 v[16:31], v[68:71], v[80:83], v[16:31]
	v_mfma_f32_32x32x16_bf16 v[0:15], v[68:71], v[64:67], v[0:15]
	v_cvt_pk_bf16_f32 v64, v212, v96
	v_cvt_pk_bf16_f32 v65, v214, v98
	v_cvt_pk_bf16_f32 v66, v216, v100
	v_cvt_pk_bf16_f32 v67, v218, v86
	v_cvt_pk_bf16_f32 v68, v213, v97
	v_cvt_pk_bf16_f32 v69, v215, v99
	v_cvt_pk_bf16_f32 v70, v217, v101
	v_cvt_pk_bf16_f32 v71, v219, v87
	ds_read_b64 v[72:73], v112 offset:9280
	ds_read_b64 v[74:75], v115 offset:9216
	s_waitcnt lgkmcnt(0)
	v_mfma_f32_32x32x16_bf16 v[48:63], v[72:75], v[64:67], v[48:63]
	v_mfma_f32_32x32x16_bf16 v[32:47], v[72:75], v[68:71], v[32:47]
	ds_read_b64 v[72:73], v116 offset:9216
	ds_read_b64 v[74:75], v117 offset:9216
	s_waitcnt lgkmcnt(0)
	v_mfma_f32_32x32x16_bf16 v[16:31], v[72:75], v[64:67], v[16:31]
	v_cvt_pk_bf16_f32 v64, v118, v104
	v_cvt_pk_bf16_f32 v65, v220, v106
	v_cvt_pk_bf16_f32 v66, v222, v108
	v_cvt_pk_bf16_f32 v67, v224, v110
	v_mfma_f32_32x32x16_bf16 v[0:15], v[72:75], v[68:71], v[0:15]
	v_cvt_pk_bf16_f32 v68, v119, v105
	v_cvt_pk_bf16_f32 v69, v221, v107
	v_cvt_pk_bf16_f32 v70, v223, v109
	v_cvt_pk_bf16_f32 v71, v225, v111
	ds_read_b64 v[72:73], v120 offset:9216
	ds_read_b64 v[74:75], v192 offset:9216
	s_waitcnt lgkmcnt(0)
	v_mfma_f32_32x32x16_bf16 v[48:63], v[72:75], v[64:67], v[48:63]
	v_mfma_f32_32x32x16_bf16 v[32:47], v[72:75], v[68:71], v[32:47]
	ds_read_b64 v[72:73], v193 offset:9216
	ds_read_b64 v[74:75], v194 offset:9216
	s_waitcnt lgkmcnt(0)
	v_mfma_f32_32x32x16_bf16 v[16:31], v[72:75], v[64:67], v[16:31]
	v_mfma_f32_32x32x16_bf16 v[0:15], v[72:75], v[68:71], v[0:15]
	s_cbranch_scc1 .LBB0_408
	v_add3_u32 v64, 0, v206, v152
	s_waitcnt vmcnt(1)
	ds_write_b128 v64, v[148:151] offset:18432
	v_add3_u32 v64, 0, v207, v208
	v_add3_u32 v65, 0, v208, v207
	s_waitcnt vmcnt(0)
	ds_write_b16 v64, v144 offset:27648
	ds_write_b16_d16_hi v65, v144 offset:27792
	ds_write_b16 v64, v145 offset:27936
	ds_write_b16_d16_hi v65, v145 offset:28080
	ds_write_b16 v64, v146 offset:28224
	ds_write_b16_d16_hi v65, v146 offset:28368
	ds_write_b16 v64, v147 offset:28512
	ds_write_b16_d16_hi v65, v147 offset:28656
	v_add_u32_e32 v144, 0, v205
	v_add_u32_e32 v102, v144, v204
	s_waitcnt lgkmcnt(0)
	s_barrier
	ds_read_b128 v[64:67], v102 offset:18432
	ds_read_b128 v[96:99], v102 offset:18464
	s_waitcnt lgkmcnt(1)
	v_mfma_f32_32x32x16_bf16 v[64:79], v[64:67], v[140:143], 0
	ds_read_b128 v[80:83], v102 offset:18496
	v_readlane_b32 s14, v203, 16
	v_readlane_b32 s15, v203, 48
	v_add_u32_e32 v145, 0x1200, v144
	v_mov_b32_e32 v100, s14
	v_mov_b32_e32 v101, s15
	v_pk_add_f32 v[100:101], s[12:13], v[100:101]
	s_mov_b32 s14, 0x3fb8aa3b
	v_add_f32_e32 v146, v100, v101
	v_mul_f32_e32 v104, 0x3fb8aa3b, v146
	v_fma_f32 v105, v146, s14, -v104
	v_rndne_f32_e32 v106, v104
	s_waitcnt lgkmcnt(1)
	v_mfma_f32_32x32x16_bf16 v[64:79], v[96:99], v[132:135], v[64:79]
	v_fmac_f32_e32 v105, 0x32a5705f, v146
	v_sub_f32_e32 v96, v104, v106
	v_add_u32_e32 v147, v145, v204
	v_add_f32_e32 v104, v96, v105
	ds_read_b128 v[96:99], v147 offset:18432
	ds_read_b128 v[100:103], v102 offset:18528
	ds_read_b128 v[112:115], v147 offset:18496
	s_waitcnt lgkmcnt(3)
	v_mfma_f32_32x32x16_bf16 v[80:95], v[80:83], v[136:139], 0
	v_readlane_b32 s12, v202, 16
	v_readlane_b32 s13, v202, 48
	s_mov_b32 s15, 0xc2ce8ed0
	v_mov_b32_e32 v116, s12
	v_mov_b32_e32 v117, s13
	v_pk_add_f32 v[116:117], s[10:11], v[116:117]
	v_cmp_ngt_f32_e32 vcc, s15, v146
	s_waitcnt lgkmcnt(1)
	v_mfma_f32_32x32x16_bf16 v[80:95], v[100:103], v[128:131], v[80:95]
	v_exp_f32_e32 v100, v104
	v_cvt_i32_f32_e32 v101, v106
	v_add_f32_e32 v149, v116, v117
	v_mul_f32_e32 v150, 0x3fb8aa3b, v149
	v_rndne_f32_e32 v151, v150
	v_ldexp_f32 v148, v100, v101
	s_mov_b32 s10, 0x42b17218
	s_waitcnt lgkmcnt(0)
; #define MFMA32(a, b, c) __builtin_amdgcn_mfma_f32_32x32x16_bf16((a), (b), (c), 0, 0, 0)
; DI void attn_pass_da(const bfr* __restrict__ P, int b, int tq_wave, int qcol, int kcol, int vcol, int key0, int nkt, char* smem, f32x16 (&o0)[2], f32x16 (&o1)[2]) {
;     ...
;     for (int t2 = 0; t2 < 2; ++t2) {
; #pragma unroll
;       for (int i = 0; i < 16; ++i) { s0[t2][i] = 0.f; s1[t2][i] = 0.f; }
; #pragma unroll
;       for (int ks = 0; ks < 2; ++ks) {
;         bf16x8 a0 = *(const bf16x8*)(sK + (t2 * 32 + r) * KP + ks * 16 + h * 8);
;         bf16x8 a1 = *(const bf16x8*)(sK + (t2 * 32 + r) * KP + 32 + ks * 16 + h * 8);
;         s0[t2] = MFMA32(a0, qf[ks], s0[t2]);
;         s1[t2] = MFMA32(a1, qf[2 + ks], s1[t2]);
;       }
;     }
;     float mx0 = s0[0][0], mx1 = s1[0][0];
; #pragma unroll
;     for (int i = 0; i < 16; ++i) { mx0 = fmaxf(mx0, fmaxf(s0[0][i], s0[1][i])); mx1 = fmaxf(mx1, fmaxf(s1[0][i], s1[1][i])); }
;     mx0 = fmaxf(mx0, __shfl_xor(mx0, 32)); mx1 = fmaxf(mx1, __shfl_xor(mx1, 32));
	v_mfma_f32_32x32x16_bf16 v[112:127], v[112:115], v[136:139], 0
	v_fma_f32 v136, v149, s14, -v150
	v_fmac_f32_e32 v136, 0x32a5705f, v149
	v_sub_f32_e32 v137, v150, v151
	v_add_f32_e32 v136, v137, v136
	v_exp_f32_e32 v150, v136
	ds_read_b128 v[136:139], v147 offset:18528
	v_readlane_b32 s12, v253, 28
	v_mfma_f32_32x32x16_bf16 v[96:111], v[96:99], v[140:143], 0
	ds_read_b128 v[140:143], v147 offset:18464
	v_readlane_b32 s13, v253, 29
	s_waitcnt lgkmcnt(0)
	v_mfma_f32_32x32x16_bf16 v[96:111], v[140:143], v[132:135], v[96:111]
	v_max_f32_e32 v134, v82, v82
	v_max_f32_e32 v135, v67, v67
	v_cvt_i32_f32_e32 v132, v151
	v_cndmask_b32_e32 v133, 0, v148, vcc
	v_cmp_nlt_f32_e32 vcc, s10, v146
	v_ldexp_f32 v132, v150, v132
	v_mfma_f32_32x32x16_bf16 v[112:127], v[136:139], v[128:131], v[112:127]
	s_nop 4
	v_max_f32_e32 v128, v97, v97
	v_max_f32_e32 v129, v65, v65
	v_max_f32_e32 v128, v129, v128
	v_max_f32_e32 v130, v81, v81
	v_max_f32_e32 v131, v66, v66
	v_max3_f32 v128, v64, v96, v128
	v_cndmask_b32_e32 v133, v201, v133, vcc
	v_max_f32_e32 v129, v113, v113
	v_max_f32_e32 v129, v130, v129
	v_max_f32_e32 v130, v98, v98
	v_max_f32_e32 v130, v131, v130
	v_max_f32_e32 v131, v114, v114
	v_max_f32_e32 v131, v134, v131
	v_max_f32_e32 v134, v99, v99
	v_max_f32_e32 v134, v135, v134
	v_max3_f32 v128, v128, v130, v134
	v_max_f32_e32 v130, v115, v115
	v_max_f32_e32 v134, v83, v83
	v_max3_f32 v129, v80, v112, v129
	v_max_f32_e32 v130, v134, v130
	v_max3_f32 v129, v129, v131, v130
	v_max_f32_e32 v130, v100, v100
	v_max_f32_e32 v131, v68, v68
	v_max_f32_e32 v130, v131, v130
	v_max_f32_e32 v131, v116, v116
	v_max_f32_e32 v134, v84, v84
	v_max_f32_e32 v131, v134, v131
	v_max_f32_e32 v134, v101, v101
	v_max_f32_e32 v135, v69, v69
	v_max_f32_e32 v134, v135, v134
	v_max3_f32 v128, v128, v130, v134
	v_max_f32_e32 v130, v117, v117
	v_max_f32_e32 v134, v85, v85
	v_max_f32_e32 v130, v134, v130
	v_max3_f32 v129, v129, v131, v130
	v_max_f32_e32 v130, v102, v102
	v_max_f32_e32 v131, v70, v70
	v_max_f32_e32 v130, v131, v130
	v_max_f32_e32 v131, v118, v118
	v_max_f32_e32 v134, v86, v86
	v_max_f32_e32 v131, v134, v131
	v_max_f32_e32 v134, v103, v103
	v_max_f32_e32 v135, v71, v71
	v_max_f32_e32 v134, v135, v134
	v_max3_f32 v128, v128, v130, v134
	v_max_f32_e32 v130, v119, v119
	v_max_f32_e32 v134, v87, v87
	v_max_f32_e32 v130, v134, v130
	v_max3_f32 v129, v129, v131, v130
	v_max_f32_e32 v130, v104, v104
	v_max_f32_e32 v131, v72, v72
	v_max_f32_e32 v130, v131, v130
	v_max_f32_e32 v131, v120, v120
	v_max_f32_e32 v134, v88, v88
	v_max_f32_e32 v131, v134, v131
	v_max_f32_e32 v134, v105, v105
	v_max_f32_e32 v135, v73, v73
	v_max_f32_e32 v134, v135, v134
	v_max3_f32 v128, v128, v130, v134
	v_max_f32_e32 v130, v121, v121
	v_max_f32_e32 v134, v89, v89
	v_max_f32_e32 v130, v134, v130
	v_max3_f32 v129, v129, v131, v130
	v_max_f32_e32 v130, v106, v106
	v_max_f32_e32 v131, v74, v74
	v_max_f32_e32 v130, v131, v130
	v_max_f32_e32 v131, v122, v122
	v_max_f32_e32 v134, v90, v90
	v_max_f32_e32 v131, v134, v131
	v_max_f32_e32 v134, v107, v107
	v_max_f32_e32 v135, v75, v75
	v_max_f32_e32 v134, v135, v134
	v_max3_f32 v128, v128, v130, v134
	v_max_f32_e32 v130, v123, v123
	v_max_f32_e32 v134, v91, v91
	v_max_f32_e32 v130, v134, v130
	v_max3_f32 v129, v129, v131, v130
	v_max_f32_e32 v130, v108, v108
	v_max_f32_e32 v131, v76, v76
	v_max_f32_e32 v130, v131, v130
	v_max_f32_e32 v131, v124, v124
	v_max_f32_e32 v134, v92, v92
	v_max_f32_e32 v131, v134, v131
	v_max_f32_e32 v134, v109, v109
	v_max_f32_e32 v135, v77, v77
	v_max_f32_e32 v134, v135, v134
	v_max3_f32 v128, v128, v130, v134
	v_max_f32_e32 v130, v125, v125
	v_max_f32_e32 v134, v93, v93
	v_max_f32_e32 v130, v134, v130
	v_max3_f32 v129, v129, v131, v130
	v_max_f32_e32 v130, v110, v110
	v_max_f32_e32 v131, v78, v78
	v_max_f32_e32 v130, v131, v130
	v_max_f32_e32 v131, v126, v126
	v_max_f32_e32 v134, v94, v94
	v_max_f32_e32 v131, v134, v131
	v_max_f32_e32 v134, v111, v111
	v_max_f32_e32 v135, v79, v79
	v_max_f32_e32 v134, v135, v134
	v_max3_f32 v128, v128, v130, v134
	v_max_f32_e32 v130, v127, v127
	v_max_f32_e32 v134, v95, v95
	v_max_f32_e32 v130, v134, v130
	v_max3_f32 v130, v129, v131, v130
	ds_bpermute_b32 v131, v166, v128
	ds_bpermute_b32 v134, v166, v130
	v_cmp_ngt_f32_e32 vcc, s15, v149
	s_waitcnt lgkmcnt(0)
; DI void attn_pass_da(const bfr* __restrict__ P, int b, int tq_wave, int qcol, int kcol, int vcol, int key0, int nkt, char* smem, f32x16 (&o0)[2], f32x16 (&o1)[2]) {
;     ...
;     const float mn0 = fmaxf(m0, mx0), mn1 = fmaxf(m1, mx1);
;     const float al0 = __builtin_amdgcn_exp2f(m0 - mn0), al1 = __builtin_amdgcn_exp2f(m1 - mn1);
;     m0 = mn0; m1 = mn1;
;     float ps0 = 0.f, ps1 = 0.f;
; #pragma unroll
;     for (int i = 0; i < 16; ++i) {
;       s0[0][i] = __builtin_amdgcn_exp2f(s0[0][i] - mn0); ps0 += s0[0][i];
;       s0[1][i] = __builtin_amdgcn_exp2f(s0[1][i] - mn0); ps0 += s0[1][i];
;       s1[0][i] = __builtin_amdgcn_exp2f(s1[0][i] - mn1); ps1 += s1[0][i];
;       s1[1][i] = __builtin_amdgcn_exp2f(s1[1][i] - mn1); ps1 += s1[1][i];
;     }
;     l0 = l0 * al0 + ps0; l1 = l1 * al1 + ps1;
; #pragma unroll
;     for (int i = 0; i < 16; ++i) { acc0[0][i] *= al0; acc0[1][i] *= al0; acc1[0][i] *= al1; acc1[1][i] *= al1; }
	v_max3_f32 v150, v210, v130, v134
	v_cndmask_b32_e32 v132, 0, v132, vcc
	v_cmp_nlt_f32_e32 vcc, s10, v149
	v_max3_f32 v149, v209, v128, v131
	v_sub_f32_e32 v64, v64, v149
	v_exp_f32_e32 v148, v64
	v_sub_f32_e32 v64, v96, v149
	v_exp_f32_e32 v131, v64
	v_sub_f32_e32 v64, v80, v150
	v_exp_f32_e32 v151, v64
	v_sub_f32_e32 v64, v112, v150
	v_exp_f32_e32 v96, v64
	v_sub_f32_e32 v64, v65, v149
	v_exp_f32_e32 v152, v64
	v_sub_f32_e32 v64, v97, v149
	v_exp_f32_e32 v112, v64
	v_sub_f32_e32 v64, v81, v150
	v_exp_f32_e32 v158, v64
	v_sub_f32_e32 v64, v113, v150
	v_exp_f32_e32 v97, v64
	v_sub_f32_e32 v64, v66, v149
	v_exp_f32_e32 v143, v64
	v_sub_f32_e32 v64, v98, v149
	v_exp_f32_e32 v113, v64
	v_sub_f32_e32 v64, v82, v150
	v_exp_f32_e32 v146, v64
	v_sub_f32_e32 v64, v114, v150
	v_exp_f32_e32 v98, v64
	v_sub_f32_e32 v64, v67, v149
	v_exp_f32_e32 v147, v64
	v_sub_f32_e32 v64, v99, v149
	v_exp_f32_e32 v114, v64
	v_sub_f32_e32 v64, v83, v150
	v_exp_f32_e32 v138, v64
	v_sub_f32_e32 v64, v115, v150
	v_exp_f32_e32 v99, v64
	v_sub_f32_e32 v64, v68, v149
	v_exp_f32_e32 v139, v64
	v_sub_f32_e32 v64, v100, v149
	v_exp_f32_e32 v115, v64
	v_sub_f32_e32 v64, v84, v150
	v_exp_f32_e32 v140, v64
	v_sub_f32_e32 v64, v116, v150
	v_exp_f32_e32 v100, v64
	v_sub_f32_e32 v64, v69, v149
	v_exp_f32_e32 v141, v64
	v_sub_f32_e32 v64, v101, v149
	v_exp_f32_e32 v116, v64
	v_sub_f32_e32 v64, v85, v150
	v_exp_f32_e32 v142, v64
	v_sub_f32_e32 v64, v117, v150
	v_exp_f32_e32 v101, v64
	v_sub_f32_e32 v64, v70, v149
	v_exp_f32_e32 v134, v64
	v_sub_f32_e32 v64, v102, v149
	v_cndmask_b32_e32 v129, v201, v132, vcc
	v_exp_f32_e32 v132, v64
	v_sub_f32_e32 v64, v86, v150
	v_exp_f32_e32 v135, v64
	v_sub_f32_e32 v64, v118, v150
	v_exp_f32_e32 v117, v64
	v_sub_f32_e32 v64, v71, v149
	v_exp_f32_e32 v136, v64
	v_sub_f32_e32 v64, v103, v149
	v_sub_f32_e32 v129, v133, v129
	v_exp_f32_e32 v133, v64
	v_sub_f32_e32 v64, v87, v150
	v_exp_f32_e32 v137, v64
	v_sub_f32_e32 v64, v119, v150
	v_exp_f32_e32 v102, v64
	v_sub_f32_e32 v64, v72, v149
	v_exp_f32_e32 v103, v64
	v_sub_f32_e32 v64, v104, v149
	v_exp_f32_e32 v71, v64
	v_sub_f32_e32 v64, v88, v150
	v_exp_f32_e32 v104, v64
	v_sub_f32_e32 v64, v120, v150
	v_exp_f32_e32 v70, v64
	v_sub_f32_e32 v64, v73, v149
	v_exp_f32_e32 v118, v64
	v_sub_f32_e32 v64, v105, v149
	v_exp_f32_e32 v73, v64
	v_sub_f32_e32 v64, v89, v150
	v_exp_f32_e32 v105, v64
	v_sub_f32_e32 v64, v121, v150
	v_exp_f32_e32 v72, v64
	v_sub_f32_e32 v64, v74, v149
	v_exp_f32_e32 v119, v64
	v_sub_f32_e32 v64, v106, v149
	v_exp_f32_e32 v81, v64
	v_sub_f32_e32 v64, v90, v150
	v_exp_f32_e32 v89, v64
	v_sub_f32_e32 v64, v122, v150
	v_exp_f32_e32 v80, v64
	v_sub_f32_e32 v64, v75, v149
	v_exp_f32_e32 v90, v64
	v_sub_f32_e32 v64, v107, v149
	v_exp_f32_e32 v87, v64
	v_sub_f32_e32 v64, v91, v150
	v_exp_f32_e32 v91, v64
	v_sub_f32_e32 v64, v123, v150
	v_exp_f32_e32 v86, v64
	v_sub_f32_e32 v64, v76, v149
	v_exp_f32_e32 v74, v64
	v_sub_f32_e32 v64, v108, v149
	v_exp_f32_e32 v75, v64
	v_sub_f32_e32 v64, v92, v150
	v_exp_f32_e32 v76, v64
	v_sub_f32_e32 v64, v124, v150
	v_exp_f32_e32 v82, v64
	v_sub_f32_e32 v64, v77, v149
	v_exp_f32_e32 v77, v64
	v_sub_f32_e32 v64, v109, v149
	v_exp_f32_e32 v83, v64
	v_sub_f32_e32 v64, v93, v150
	v_exp_f32_e32 v84, v64
	v_sub_f32_e32 v64, v125, v150
	v_exp_f32_e32 v85, v64
	v_sub_f32_e32 v64, v78, v149
	v_exp_f32_e32 v78, v64
	v_sub_f32_e32 v64, v110, v149
	v_exp_f32_e32 v88, v64
	v_sub_f32_e32 v64, v94, v150
	v_exp_f32_e32 v66, v64
	v_sub_f32_e32 v64, v126, v150
	v_exp_f32_e32 v67, v64
	v_sub_f32_e32 v64, v79, v149
	v_exp_f32_e32 v68, v64
	v_sub_f32_e32 v64, v111, v149
	v_lshl_add_u32 v79, v181, 1, v144
	v_lshl_add_u32 v110, v180, 1, v144
	v_lshl_add_u32 v124, v179, 1, v145
	v_lshl_add_u32 v126, v178, 1, v145
	v_exp_f32_e32 v69, v64
	v_sub_f32_e32 v64, v95, v150
	v_sub_f32_e32 v65, v127, v150
	v_cvt_pk_bf16_f32 v92, v148, v152
	v_cvt_pk_bf16_f32 v93, v143, v147
	v_cvt_pk_bf16_f32 v94, v139, v141
	v_cvt_pk_bf16_f32 v95, v134, v136
	v_cvt_pk_bf16_f32 v106, v151, v158
	v_cvt_pk_bf16_f32 v107, v146, v138
	v_cvt_pk_bf16_f32 v108, v140, v142
	v_cvt_pk_bf16_f32 v109, v135, v137
	ds_read_b64 v[120:121], v79 offset:27648
	ds_read_b64 v[122:123], v110 offset:27648
	ds_read_b64 v[124:125], v124 offset:27648
	ds_read_b64 v[126:127], v126 offset:27648
	v_sub_f32_e32 v128, v209, v149
	v_exp_f32_e32 v130, v128
	v_sub_f32_e32 v128, v210, v150
	v_add_f32_e32 v111, 0, v151
	v_exp_f32_e32 v128, v128
	v_add_f32_e32 v110, 0, v148
	v_add_f32_e32 v111, v96, v111
	v_add_f32_e32 v110, v131, v110
	v_add_f32_e32 v111, v158, v111
	v_add_f32_e32 v110, v152, v110
	v_add_f32_e32 v111, v97, v111
	v_add_f32_e32 v110, v112, v110
	v_add_f32_e32 v111, v146, v111
	v_pk_mul_f32 v[46:47], v[46:47], v[128:129] op_sel_hi:[1,0]
	v_pk_mul_f32 v[44:45], v[44:45], v[128:129] op_sel_hi:[1,0]
	v_pk_mul_f32 v[42:43], v[42:43], v[128:129] op_sel_hi:[1,0]
	v_pk_mul_f32 v[40:41], v[40:41], v[128:129] op_sel_hi:[1,0]
	v_pk_mul_f32 v[38:39], v[38:39], v[128:129] op_sel_hi:[1,0]
	v_pk_mul_f32 v[36:37], v[36:37], v[128:129] op_sel_hi:[1,0]
	v_pk_mul_f32 v[34:35], v[34:35], v[128:129] op_sel_hi:[1,0]
	v_pk_mul_f32 v[32:33], v[32:33], v[128:129] op_sel_hi:[1,0]
	v_pk_mul_f32 v[14:15], v[14:15], v[128:129] op_sel_hi:[1,0]
	v_pk_mul_f32 v[12:13], v[12:13], v[128:129] op_sel_hi:[1,0]
	v_pk_mul_f32 v[10:11], v[10:11], v[128:129] op_sel_hi:[1,0]
	v_pk_mul_f32 v[8:9], v[8:9], v[128:129] op_sel_hi:[1,0]
	v_pk_mul_f32 v[6:7], v[6:7], v[128:129] op_sel_hi:[1,0]
	v_pk_mul_f32 v[4:5], v[4:5], v[128:129] op_sel_hi:[1,0]
	v_pk_mul_f32 v[2:3], v[2:3], v[128:129] op_sel_hi:[1,0]
	v_pk_mul_f32 v[0:1], v[0:1], v[128:129] op_sel_hi:[1,0]
	v_add_f32_e32 v110, v143, v110
	v_add_f32_e32 v111, v98, v111
	s_waitcnt lgkmcnt(2)
; #define MFMA32(a, b, c) __builtin_amdgcn_mfma_f32_32x32x16_bf16((a), (b), (c), 0, 0, 0)
; DI unsigned pack2(float a, float b) { unsigned r; asm volatile("v_cvt_pk_bf16_f32 %0, %1, %2" : "=v"(r) : "v"(a), "v"(b)); return r; }
; DI void attn_pass_da(const bfr* __restrict__ P, int b, int tq_wave, int qcol, int kcol, int vcol, int key0, int nkt, char* smem, f32x16 (&o0)[2], f32x16 (&o1)[2]) {
;     ...
;     float ps0 = 0.f, ps1 = 0.f;
; #pragma unroll
;     for (int i = 0; i < 16; ++i) {
;       s0[0][i] = __builtin_amdgcn_exp2f(s0[0][i] - mn0); ps0 += s0[0][i];
;       s0[1][i] = __builtin_amdgcn_exp2f(s0[1][i] - mn0); ps0 += s0[1][i];
;       s1[0][i] = __builtin_amdgcn_exp2f(s1[0][i] - mn1); ps1 += s1[0][i];
;       s1[1][i] = __builtin_amdgcn_exp2f(s1[1][i] - mn1); ps1 += s1[1][i];
;     }
;     l0 = l0 * al0 + ps0; l1 = l1 * al1 + ps1;
; #pragma unroll
;     for (int i = 0; i < 16; ++i) { acc0[0][i] *= al0; acc0[1][i] *= al0; acc1[0][i] *= al1; acc1[1][i] *= al1; }
; #pragma unroll
;     for (int t2 = 0; t2 < 2; ++t2)
; #pragma unroll
;       for (int j = 0; j < 2; ++j) {
;         u32x4 pk0, pk1;
;         pk0.x = pack2(s0[t2][8 * j + 0], s0[t2][8 * j + 1]); pk0.y = pack2(s0[t2][8 * j + 2], s0[t2][8 * j + 3]);
;         pk0.z = pack2(s0[t2][8 * j + 4], s0[t2][8 * j + 5]); pk0.w = pack2(s0[t2][8 * j + 6], s0[t2][8 * j + 7]);
;         pk1.x = pack2(s1[t2][8 * j + 0], s1[t2][8 * j + 1]); pk1.y = pack2(s1[t2][8 * j + 2], s1[t2][8 * j + 3]);
;         pk1.z = pack2(s1[t2][8 * j + 4], s1[t2][8 * j + 5]); pk1.w = pack2(s1[t2][8 * j + 6], s1[t2][8 * j + 7]);
;         const bf16x8 pf0 = __builtin_bit_cast(bf16x8, pk0), pf1 = __builtin_bit_cast(bf16x8, pk1);
; #pragma unroll
;         for (int dt = 0; dt < 2; ++dt) {
;           const int vsw = (((dt * 32 + r) >> 3) & 7) << 3;
;           const bfr* vrow = sV + (dt * 32 + r) * 72;
;           s16x4 lo = *(const s16x4*)(vrow + ((t2 * 32 + 16 * j + 4 * h) ^ vsw));
;           s16x4 hi = *(const s16x4*)(vrow + ((t2 * 32 + 16 * j + 4 * h + 8) ^ vsw));
;           bf16x8 vf = __builtin_shufflevector(lo, hi, 0, 1, 2, 3, 4, 5, 6, 7);
;           acc0[dt] = MFMA32(vf, pf0, acc0[dt]);
;           acc1[dt] = MFMA32(vf, pf1, acc1[dt]);
;         }
;       }
;   }
;   l0 += __shfl_xor(l0, 32); l1 += __shfl_xor(l1, 32);
;   const float i0 = 1.f / l0, i1 = 1.f / l1;
	v_mfma_f32_32x32x16_bf16 v[32:47], v[120:123], v[106:109], v[32:47]
	v_add_f32_e32 v110, v113, v110
	v_add_f32_e32 v110, v147, v110
	v_add_f32_e32 v110, v114, v110
	v_mul_f32_e64 v62, v62, v130
	v_mul_f32_e64 v63, v63, v130
	v_pk_mul_f32 v[60:61], v[60:61], v[130:131] op_sel_hi:[1,0]
	v_pk_mul_f32 v[58:59], v[58:59], v[130:131] op_sel_hi:[1,0]
	v_pk_mul_f32 v[56:57], v[56:57], v[130:131] op_sel_hi:[1,0]
	s_waitcnt lgkmcnt(0)
	v_mfma_f32_32x32x16_bf16 v[0:15], v[124:127], v[106:109], v[0:15]
	v_add_f32_e32 v106, v138, v111
	v_add_f32_e32 v106, v99, v106
	v_add_f32_e32 v106, v140, v106
	v_add_f32_e32 v107, v139, v110
	v_add_f32_e32 v106, v100, v106
	v_add_f32_e32 v107, v115, v107
	v_add_f32_e32 v106, v142, v106
	v_pk_mul_f32 v[54:55], v[54:55], v[130:131] op_sel_hi:[1,0]
	v_pk_mul_f32 v[52:53], v[52:53], v[130:131] op_sel_hi:[1,0]
	v_pk_mul_f32 v[50:51], v[50:51], v[130:131] op_sel_hi:[1,0]
	v_pk_mul_f32 v[48:49], v[48:49], v[130:131] op_sel_hi:[1,0]
	v_pk_mul_f32 v[30:31], v[30:31], v[130:131] op_sel_hi:[1,0]
	v_pk_mul_f32 v[28:29], v[28:29], v[130:131] op_sel_hi:[1,0]
	v_pk_mul_f32 v[26:27], v[26:27], v[130:131] op_sel_hi:[1,0]
	v_pk_mul_f32 v[24:25], v[24:25], v[130:131] op_sel_hi:[1,0]
	v_pk_mul_f32 v[22:23], v[22:23], v[130:131] op_sel_hi:[1,0]
	v_pk_mul_f32 v[20:21], v[20:21], v[130:131] op_sel_hi:[1,0]
	v_pk_mul_f32 v[18:19], v[18:19], v[130:131] op_sel_hi:[1,0]
	v_pk_mul_f32 v[16:17], v[16:17], v[130:131] op_sel_hi:[1,0]
	v_lshl_add_u32 v143, v177, 1, v144
	v_add_f32_e32 v107, v141, v107
	v_add_f32_e32 v111, v101, v106
	v_lshl_add_u32 v106, v175, 1, v145
	v_lshl_add_u32 v108, v174, 1, v145
	v_exp_f32_e32 v64, v64
	v_mfma_f32_32x32x16_bf16 v[48:63], v[120:123], v[92:95], v[48:63]
	v_add_f32_e32 v110, v116, v107
	v_add_f32_e32 v110, v134, v110
	v_add_f32_e32 v110, v132, v110
	v_add_f32_e32 v110, v136, v110
	v_add_f32_e32 v111, v135, v111
	v_add_f32_e32 v111, v117, v111
	v_exp_f32_e32 v65, v65
	v_mfma_f32_32x32x16_bf16 v[16:31], v[124:127], v[92:95], v[16:31]
	v_cvt_pk_bf16_f32 v92, v103, v118
	v_cvt_pk_bf16_f32 v93, v119, v90
	v_cvt_pk_bf16_f32 v94, v74, v77
	v_cvt_pk_bf16_f32 v95, v78, v68
	v_cvt_pk_bf16_f32 v120, v104, v105
	v_cvt_pk_bf16_f32 v121, v89, v91
	v_cvt_pk_bf16_f32 v122, v76, v84
	v_cvt_pk_bf16_f32 v123, v66, v64
	ds_read_b64 v[146:147], v143 offset:27648
	ds_read_b64 v[106:107], v106 offset:27648
	ds_read_b64 v[108:109], v108 offset:27648
	v_lshl_add_u32 v143, v176, 1, v144
	ds_read_b64 v[148:149], v143 offset:27648
	v_add_f32_e32 v124, v133, v110
	s_waitcnt lgkmcnt(0)
	v_mfma_f32_32x32x16_bf16 v[48:63], v[146:149], v[92:95], v[48:63]
	v_add_f32_e32 v125, v137, v111
	v_lshlrev_b32_e32 v152, 1, v154
	v_mfma_f32_32x32x16_bf16 v[16:31], v[106:109], v[92:95], v[16:31]
	v_cvt_pk_bf16_f32 v92, v131, v112
	v_cvt_pk_bf16_f32 v93, v113, v114
	v_cvt_pk_bf16_f32 v94, v115, v116
	v_cvt_pk_bf16_f32 v95, v132, v133
	v_cvt_pk_bf16_f32 v96, v96, v97
	v_cvt_pk_bf16_f32 v97, v98, v99
	v_cvt_pk_bf16_f32 v98, v100, v101
	v_add_f32_e32 v100, v103, v124
	v_add_f32_e32 v100, v71, v100
	v_cvt_pk_bf16_f32 v99, v117, v102
	ds_read_b64 v[110:111], v79 offset:27712
	v_lshl_add_u32 v79, v173, 1, v144
	v_add_f32_e32 v100, v118, v100
	ds_read_b64 v[112:113], v79 offset:27648
	v_add_f32_e32 v79, v102, v125
	v_add_f32_e32 v100, v73, v100
	v_add_f32_e32 v79, v104, v79
	v_add_f32_e32 v104, v119, v100
	v_lshl_add_u32 v100, v172, 1, v145
	v_lshl_add_u32 v102, v171, 1, v145
	ds_read_b64 v[100:101], v100 offset:27648
	ds_read_b64 v[102:103], v102 offset:27648
	v_add_f32_e32 v79, v70, v79
	v_add_f32_e32 v79, v105, v79
	v_add_f32_e32 v79, v72, v79
	v_add_f32_e32 v104, v81, v104
	v_add_f32_e32 v79, v89, v79
	v_add_f32_e32 v79, v80, v79
	v_add_f32_e32 v89, v90, v104
	v_add_f32_e32 v89, v87, v89
	v_add_f32_e32 v79, v91, v79
	v_add_f32_e32 v79, v86, v79
	v_add_f32_e32 v74, v74, v89
	s_waitcnt lgkmcnt(2)
	v_mfma_f32_32x32x16_bf16 v[48:63], v[110:113], v[92:95], v[48:63]
	v_cvt_pk_bf16_f32 v90, v71, v73
	v_cvt_pk_bf16_f32 v91, v81, v87
	v_add_f32_e32 v74, v75, v74
	v_add_f32_e32 v74, v77, v74
	v_add_f32_e32 v74, v83, v74
	v_add_f32_e32 v74, v78, v74
	v_add_f32_e32 v78, v88, v74
	s_waitcnt lgkmcnt(0)
	v_mfma_f32_32x32x16_bf16 v[16:31], v[100:103], v[92:95], v[16:31]
	v_cvt_pk_bf16_f32 v92, v75, v83
	v_add_f32_e32 v75, v76, v79
	v_add_f32_e32 v75, v82, v75
	v_add_f32_e32 v75, v84, v75
	v_add_f32_e32 v79, v85, v75
	v_add_f32_e32 v66, v66, v79
	v_cvt_pk_bf16_f32 v93, v88, v69
	v_mfma_f32_32x32x16_bf16 v[32:47], v[146:149], v[120:123], v[32:47]
	v_cvt_pk_bf16_f32 v70, v70, v72
	v_cvt_pk_bf16_f32 v71, v80, v86
	v_cvt_pk_bf16_f32 v72, v82, v85
	v_cvt_pk_bf16_f32 v73, v67, v65
	v_add_f32_e32 v66, v67, v66
	v_add_f32_e32 v67, v68, v78
	v_add_f32_e32 v67, v69, v67
	v_mfma_f32_32x32x16_bf16 v[0:15], v[106:109], v[120:123], v[0:15]
	v_fmac_f32_e32 v67, v156, v130
	ds_bpermute_b32 v68, v166, v67
	v_lshl_add_u32 v80, v169, 1, v144
	v_lshl_add_u32 v74, v168, 1, v145
	v_lshl_add_u32 v76, v167, 1, v145
	ds_read_b64 v[104:105], v80 offset:27648
	ds_read_b64 v[74:75], v74 offset:27648
	ds_read_b64 v[76:77], v76 offset:27648
	v_lshl_add_u32 v80, v170, 1, v144
	v_add_f32_e32 v64, v64, v66
	ds_read_b64 v[106:107], v80 offset:27648
	v_add_f32_e32 v65, v65, v64
	v_mfma_f32_32x32x16_bf16 v[32:47], v[110:113], v[96:99], v[32:47]
	v_fmac_f32_e32 v65, v157, v128
	s_waitcnt lgkmcnt(4)
	v_add_f32_e32 v66, v67, v68
	ds_bpermute_b32 v67, v166, v65
	v_div_scale_f32 v68, s[10:11], v66, v66, 1.0
	v_rcp_f32_e32 v69, v68
	v_add_f32_e32 v64, v155, v129
	v_mfma_f32_32x32x16_bf16 v[0:15], v[100:103], v[96:99], v[0:15]
	s_waitcnt lgkmcnt(0)
; DI int otid() { int t = threadIdx.x & 255; asm volatile("" : "+v"(t)); return t; }
; DI int oidx(int i) { asm volatile("" : "+s"(i)); return i; }
; DI int vhalf() { int h = __builtin_amdgcn_readfirstlane(threadIdx.x >> 8); asm volatile("" : "+s"(h)); return h; }
; DI void attn_pass_da(const bfr* __restrict__ P, int b, int tq_wave, int qcol, int kcol, int vcol, int key0, int nkt, char* smem, f32x16 (&o0)[2], f32x16 (&o1)[2]) {
;     ...
;   const float i0 = 1.f / l0, i1 = 1.f / l1;
; #pragma unroll
;   for (int i = 0; i < 16; ++i) { o0[0][i] = acc0[0][i] * i0; o0[1][i] = acc0[1][i] * i0; o1[0][i] = acc1[0][i] * i1; o1[1][i] = acc1[1][i] * i1; }
; }
; DI void store_o(bfr* O, int m, int colbase, int h, const f32x16 (&o)[2]) {
; #pragma unroll
;   for (int dt = 0; dt < 2; ++dt)
; #pragma unroll
;     for (int g4 = 0; g4 < 4; ++g4) {
;       int dv = dt * 32 + 8 * g4 + 4 * h;
;       uint2 pk; pk.x = pack2(o[dt][4 * g4], o[dt][4 * g4 + 1]); pk.y = pack2(o[dt][4 * g4 + 2], o[dt][4 * g4 + 3]);
;       *(uint2*)(O + (size_t)m * DM + colbase + dv) = pk;
;     }
; }
; DN void da_item(const Params& p, int l, int b, int hd, int tq0, int key0, int nkt, char* smem) {
;   const bfr* P = (const bfr*)(p.ws + OFF_P);
;   bfr* O = (bfr*)(p.ws + OFF_HO);
;   const int tid = otid(), lane = tid & 63, w = tid >> 6, r = lane & 31, h = lane >> 5;
;   const float* lv = p.in[oidx(22)] + l * 128;
;   float d01 = (lane < 32) ? lv[lane] * lv[32 + lane] : 0.f;
;   float d23 = (lane < 32) ? lv[64 + lane] * lv[96 + lane] : 0.f;
;   d01 = wave_sum(d01); d23 = wave_sum(d23);
;   float lam_init = 0.8f - 0.6f * expf(-0.3f * (float)l);
;   float lam = expf(d01) - expf(d23) + lam_init;
;   f32x16 o0[2], o1[2];
;   int tqw = tq0 + vhalf() * 128 + w * 32;
;   attn_pass_da(P, b, tqw, 1152 + hd * 64, 1408 + hd * 64, 1664 + hd * 64, key0, nkt, smem, o0, o1);
;   float ss = 0.f;
; #pragma unroll
;   for (int dt = 0; dt < 2; ++dt)
; #pragma unroll
;     for (int i = 0; i < 16; ++i) { float v = o0[dt][i] - lam * o1[dt][i]; o0[dt][i] = v; ss += v * v; }
;   ss += __shfl_xor(ss, 32);
;   float rstd = rsqrtf(ss * (1.f / 64.f) + 1e-6f) * (1.f - lam_init);
;   const float* sg = p.in[oidx(23)] + l * 64;
; #pragma unroll
;   for (int dt = 0; dt < 2; ++dt)
; #pragma unroll
;     for (int i = 0; i < 16; ++i) { int dv = dt * 32 + 8 * (i >> 2) + 4 * h + (i & 3); o0[dt][i] = o0[dt][i] * rstd * sg[dv]; }
	v_add_f32_e32 v65, v65, v67
	v_fma_f32 v67, -v68, v69, 1.0
	v_fmac_f32_e32 v69, v67, v69
	v_div_scale_f32 v67, vcc, 1.0, v66, 1.0
	v_mfma_f32_32x32x16_bf16 v[32:47], v[104:107], v[70:73], v[32:47]
	v_mfma_f32_32x32x16_bf16 v[0:15], v[74:77], v[70:73], v[0:15]
	v_mul_f32_e32 v70, v67, v69
	v_fma_f32 v71, -v68, v70, v67
	v_fmac_f32_e32 v70, v71, v69
	v_fma_f32 v67, -v68, v70, v67
	v_div_scale_f32 v68, s[10:11], v65, v65, 1.0
	v_rcp_f32_e32 v71, v68
	v_div_fmas_f32 v67, v67, v69, v70
	v_div_fixup_f32 v66, v67, v66, 1.0
	v_mfma_f32_32x32x16_bf16 v[48:63], v[104:107], v[90:93], v[48:63]
	v_fma_f32 v67, -v68, v71, 1.0
	v_fmac_f32_e32 v71, v67, v71
	v_div_scale_f32 v67, vcc, 1.0, v65, 1.0
	v_mul_f32_e32 v69, v67, v71
	v_fma_f32 v70, -v68, v69, v67
	v_fmac_f32_e32 v69, v70, v71
	v_fma_f32 v67, -v68, v69, v67
	v_div_fmas_f32 v67, v67, v71, v69
	v_div_fixup_f32 v68, v67, v65, 1.0
	v_mul_f32_e32 v65, v0, v68
	v_mul_f32_e32 v0, v33, v68
	v_mul_f32_e32 v67, v1, v68
	v_mul_f32_e32 v1, v34, v68
	v_mul_f32_e32 v0, v64, v0
	v_mul_f32_e32 v32, v32, v68
	v_mul_f32_e32 v69, v2, v68
	v_mul_f32_e32 v2, v35, v68
	v_mul_f32_e32 v33, v37, v68
	v_mul_f32_e32 v37, v41, v68
	v_mul_f32_e32 v41, v45, v68
	v_fma_f32 v45, v49, v66, -v0
	v_mul_f32_e32 v0, v64, v1
	v_mul_f32_e32 v70, v3, v68
	v_mul_f32_e32 v3, v36, v68
	v_mul_f32_e32 v35, v39, v68
	v_mul_f32_e32 v39, v43, v68
	v_mul_f32_e32 v43, v47, v68
	v_mul_f32_e32 v32, v64, v32
	v_fma_f32 v47, v50, v66, -v0
	v_mul_f32_e32 v0, v64, v2
	v_mul_f32_e32 v36, v40, v68
	v_mul_f32_e32 v40, v44, v68
	v_fma_f32 v44, v48, v66, -v32
	v_fma_f32 v48, v51, v66, -v0
	v_mul_f32_e32 v0, v64, v3
	v_mul_f32_e32 v34, v38, v68
	v_fma_f32 v49, v52, v66, -v0
	v_mul_f32_e32 v0, v64, v33
	s_mov_b32 s10, 23
	v_fma_f32 v50, v53, v66, -v0
	v_mul_f32_e32 v0, v64, v34
	s_ashr_i32 s11, s10, 31
	v_fma_f32 v51, v54, v66, -v0
	v_mul_f32_e32 v0, v64, v35
	s_lshl_b64 s[10:11], s[10:11], 3
	v_fma_f32 v52, v55, v66, -v0
	v_mul_f32_e32 v0, v64, v36
	s_add_u32 s10, s0, s10
	v_mul_f32_e32 v38, v42, v68
	v_fma_f32 v53, v56, v66, -v0
	v_mul_f32_e32 v0, v64, v37
	s_addc_u32 s11, s1, s11
	v_fma_f32 v54, v57, v66, -v0
	v_mul_f32_e32 v0, v64, v38
	s_load_dwordx2 s[10:11], s[10:11], 0x0
	v_mul_f32_e32 v42, v46, v68
	v_mul_f32_e32 v46, v45, v45
	v_fma_f32 v55, v58, v66, -v0
	v_mul_f32_e32 v0, v64, v39
	v_fmac_f32_e32 v46, v44, v44
	v_fma_f32 v56, v59, v66, -v0
	v_mul_f32_e32 v0, v64, v40
	v_fmac_f32_e32 v46, v47, v47
	v_fma_f32 v57, v60, v66, -v0
	v_mul_f32_e32 v0, v64, v41
	v_fmac_f32_e32 v46, v48, v48
	v_fma_f32 v58, v61, v66, -v0
	s_lshl_b64 s[12:13], s[12:13], 2
	v_lshrrev_b32_e32 v0, 3, v164
	v_fmac_f32_e32 v46, v49, v49
	s_waitcnt lgkmcnt(0)
	s_add_u32 s10, s10, s12
	v_and_b32_e32 v59, 4, v0
	v_fmac_f32_e32 v46, v50, v50
	s_addc_u32 s11, s11, s13
	v_lshlrev_b32_e32 v60, 2, v59
	v_mfma_f32_32x32x16_bf16 v[16:31], v[74:77], v[90:93], v[16:31]
	v_fmac_f32_e32 v46, v51, v51
	global_load_dwordx4 v[0:3], v60, s[10:11]
	v_fmac_f32_e32 v46, v52, v52
	v_fmac_f32_e32 v46, v53, v53
	v_mul_f32_e32 v32, v64, v42
	v_fmac_f32_e32 v46, v54, v54
	v_fma_f32 v61, v62, v66, -v32
	v_mul_f32_e32 v32, v64, v43
	v_fmac_f32_e32 v46, v55, v55
	v_fma_f32 v62, v63, v66, -v32
	global_load_dwordx4 v[32:35], v60, s[10:11] offset:32
	v_fmac_f32_e32 v46, v56, v56
	v_fmac_f32_e32 v46, v57, v57
	v_fmac_f32_e32 v46, v58, v58
	v_mul_f32_e32 v36, v64, v65
	v_fmac_f32_e32 v46, v61, v61
	v_fma_f32 v63, v16, v66, -v36
	v_mul_f32_e32 v16, v64, v67
	global_load_dwordx4 v[36:39], v60, s[10:11] offset:64
	v_mul_f32_e32 v4, v4, v68
	v_fmac_f32_e32 v46, v62, v62
	v_fma_f32 v65, v17, v66, -v16
	v_mul_f32_e32 v16, v64, v69
	v_mul_f32_e32 v5, v5, v68
	v_fmac_f32_e32 v46, v63, v63
	v_fma_f32 v67, v18, v66, -v16
	v_mul_f32_e32 v16, v64, v70
	v_mul_f32_e32 v4, v64, v4
	v_fmac_f32_e32 v46, v65, v65
	v_fma_f32 v69, v19, v66, -v16
	v_fma_f32 v70, v20, v66, -v4
	v_mul_f32_e32 v4, v64, v5
	v_fmac_f32_e32 v46, v67, v67
	global_load_dwordx4 v[16:19], v60, s[10:11] offset:96
	v_fma_f32 v71, v21, v66, -v4
	v_pk_mul_f32 v[4:5], v[6:7], v[68:69] op_sel_hi:[1,0]
	v_fmac_f32_e32 v46, v69, v69
	v_pk_mul_f32 v[4:5], v[64:65], v[4:5] op_sel_hi:[0,1]
	v_fmac_f32_e32 v46, v70, v70
	v_pk_fma_f32 v[40:41], v[22:23], v[66:67], v[4:5] op_sel_hi:[1,0,1] neg_lo:[0,0,1] neg_hi:[0,0,1]
	v_pk_mul_f32 v[8:9], v[8:9], v[68:69] op_sel_hi:[1,0]
	v_fmac_f32_e32 v46, v71, v71
	v_pk_mul_f32 v[20:21], v[40:41], v[40:41]
	v_pk_mul_f32 v[8:9], v[64:65], v[8:9] op_sel_hi:[0,1]
	global_load_dwordx4 v[4:7], v60, s[10:11] offset:128
	v_add_f32_e32 v20, v20, v46
	v_pk_fma_f32 v[24:25], v[24:25], v[66:67], v[8:9] op_sel_hi:[1,0,1] neg_lo:[0,0,1] neg_hi:[0,0,1]
	v_add_f32_e32 v20, v21, v20
	v_pk_mul_f32 v[8:9], v[24:25], v[24:25]
	v_pk_mul_f32 v[12:13], v[12:13], v[68:69] op_sel_hi:[1,0]
	v_add_f32_e32 v8, v8, v20
	v_add_f32_e32 v42, v9, v8
	v_pk_mul_f32 v[8:9], v[10:11], v[68:69] op_sel_hi:[1,0]
	global_load_dwordx4 v[20:23], v60, s[10:11] offset:160
	v_pk_mul_f32 v[8:9], v[64:65], v[8:9] op_sel_hi:[0,1]
	v_pk_fma_f32 v[26:27], v[26:27], v[66:67], v[8:9] op_sel_hi:[1,0,1] neg_lo:[0,0,1] neg_hi:[0,0,1]
	v_pk_mul_f32 v[12:13], v[64:65], v[12:13] op_sel_hi:[0,1]
	v_pk_mul_f32 v[8:9], v[26:27], v[26:27]
	v_pk_fma_f32 v[28:29], v[28:29], v[66:67], v[12:13] op_sel_hi:[1,0,1] neg_lo:[0,0,1] neg_hi:[0,0,1]
	v_add_f32_e32 v8, v8, v42
	v_add_f32_e32 v42, v9, v8
	global_load_dwordx4 v[8:11], v60, s[10:11] offset:192
	v_pk_mul_f32 v[12:13], v[28:29], v[28:29]
	s_load_dwordx4 s[12:15], s[0:1], 0x100
	v_add_f32_e32 v12, v12, v42
	v_add_f32_e32 v46, v13, v12
	v_pk_mul_f32 v[42:43], v[14:15], v[68:69] op_sel_hi:[1,0]
	global_load_dwordx4 v[12:15], v60, s[10:11] offset:224
	v_pk_mul_f32 v[42:43], v[64:65], v[42:43] op_sel_hi:[0,1]
	v_pk_fma_f32 v[30:31], v[30:31], v[66:67], v[42:43] op_sel_hi:[1,0,1] neg_lo:[0,0,1] neg_hi:[0,0,1]
	s_mov_b64 s[10:11], 0x2b7c300
	v_pk_mul_f32 v[42:43], v[30:31], v[30:31]
	s_nop 0
	v_add_f32_e32 v42, v42, v46
	v_add_f32_e32 v42, v43, v42
	ds_bpermute_b32 v43, v166, v42
	s_waitcnt lgkmcnt(0)
; DI int oidx(int i) { asm volatile("" : "+s"(i)); return i; }
; DI unsigned pack2(float a, float b) { unsigned r; asm volatile("v_cvt_pk_bf16_f32 %0, %1, %2" : "=v"(r) : "v"(a), "v"(b)); return r; }
; DI void store_o(bfr* O, int m, int colbase, int h, const f32x16 (&o)[2]) {
; #pragma unroll
;   for (int dt = 0; dt < 2; ++dt)
; #pragma unroll
;     for (int g4 = 0; g4 < 4; ++g4) {
;       int dv = dt * 32 + 8 * g4 + 4 * h;
;       uint2 pk; pk.x = pack2(o[dt][4 * g4], o[dt][4 * g4 + 1]); pk.y = pack2(o[dt][4 * g4 + 2], o[dt][4 * g4 + 3]);
;       *(uint2*)(O + (size_t)m * DM + colbase + dv) = pk;
;     }
; }
; DN void da_item(const Params& p, int l, int b, int hd, int tq0, int key0, int nkt, char* smem) {
;     ...
;   ss += __shfl_xor(ss, 32);
;   float rstd = rsqrtf(ss * (1.f / 64.f) + 1e-6f) * (1.f - lam_init);
;   const float* sg = p.in[oidx(23)] + l * 64;
; #pragma unroll
;   for (int dt = 0; dt < 2; ++dt)
; #pragma unroll
;     for (int i = 0; i < 16; ++i) { int dv = dt * 32 + 8 * (i >> 2) + 4 * h + (i & 3); o0[dt][i] = o0[dt][i] * rstd * sg[dv]; }
;   store_o(O, b * TT + tqw + r, 256 + hd * 64, h, o0);
	v_add_f32_e32 v42, v42, v43
	v_fmamk_f32 v42, v42, 0x3c800000, v186
	v_cmp_gt_f32_e32 vcc, s33, v42
	v_mul_f32_e32 v43, 0x4b800000, v42
	s_nop 0
	v_cndmask_b32_e32 v42, v42, v43, vcc
	v_rsq_f32_e32 v42, v42
	s_nop 0
	v_mul_f32_e32 v43, 0x45800000, v42
	v_cndmask_b32_e32 v42, v42, v43, vcc
	v_mul_f32_e32 v42, v162, v42
	v_mul_f32_e32 v43, v44, v42
	s_waitcnt vmcnt(7)
	v_mul_f32_e32 v43, v0, v43
	v_mul_f32_e32 v0, v45, v42
	v_mul_f32_e32 v44, v1, v0
	v_mul_f32_e32 v0, v47, v42
	v_mul_f32_e32 v45, v2, v0
	v_mul_f32_e32 v0, v48, v42
	v_mul_f32_e32 v3, v3, v0
	v_mul_f32_e32 v0, v49, v42
	s_waitcnt vmcnt(6)
	v_mul_f32_e32 v32, v32, v0
	v_mul_f32_e32 v0, v50, v42
	v_mul_f32_e32 v33, v33, v0
	v_mul_f32_e32 v0, v51, v42
	v_mul_f32_e32 v34, v34, v0
	v_mul_f32_e32 v0, v52, v42
	v_mul_f32_e32 v35, v35, v0
	v_mul_f32_e32 v0, v53, v42
	s_waitcnt vmcnt(5)
	v_mul_f32_e32 v36, v36, v0
	v_mul_f32_e32 v0, v54, v42
	v_mul_f32_e32 v37, v37, v0
	v_mul_f32_e32 v0, v55, v42
	v_mul_f32_e32 v38, v38, v0
	v_mul_f32_e32 v0, v56, v42
	v_mul_f32_e32 v39, v39, v0
	v_mul_f32_e32 v0, v57, v42
	s_waitcnt vmcnt(4)
	v_mul_f32_e32 v16, v16, v0
	v_mul_f32_e32 v0, v58, v42
	v_mul_f32_e32 v17, v17, v0
	v_mul_f32_e32 v0, v61, v42
	v_mul_f32_e32 v18, v18, v0
	v_mul_f32_e32 v0, v62, v42
	v_mul_f32_e32 v19, v19, v0
	v_mul_f32_e32 v0, v63, v42
	s_waitcnt vmcnt(3)
	v_mul_f32_e32 v46, v4, v0
	v_mul_f32_e32 v0, v65, v42
	v_mul_f32_e32 v47, v5, v0
	v_mul_f32_e32 v0, v67, v42
	v_mul_f32_e32 v6, v6, v0
	v_mul_f32_e32 v0, v69, v42
	v_mul_f32_e32 v7, v7, v0
	v_mul_f32_e32 v0, v70, v42
	s_waitcnt vmcnt(2)
	v_mul_f32_e32 v20, v20, v0
	v_mul_f32_e32 v0, v71, v42
	v_mul_f32_e32 v21, v21, v0
	v_mul_f32_e32 v0, v40, v42
	v_mul_f32_e32 v22, v22, v0
	v_mul_f32_e32 v0, v41, v42
	v_mul_f32_e32 v23, v23, v0
	v_mul_f32_e32 v0, v24, v42
	s_waitcnt vmcnt(1)
	v_mul_f32_e32 v8, v8, v0
	v_mul_f32_e32 v0, v25, v42
	v_mul_f32_e32 v9, v9, v0
	v_mul_f32_e32 v0, v26, v42
	v_mul_f32_e32 v10, v10, v0
	v_mul_f32_e32 v0, v27, v42
	v_mul_f32_e32 v11, v11, v0
	v_mul_f32_e32 v0, v28, v42
	s_waitcnt vmcnt(0)
	v_mul_f32_e32 v12, v12, v0
	v_mul_f32_e32 v0, v29, v42
	v_mul_f32_e32 v13, v13, v0
	v_mul_f32_e32 v0, v30, v42
	v_mul_f32_e32 v14, v14, v0
	v_mul_f32_e32 v0, v31, v42
	v_mul_f32_e32 v15, v15, v0
	v_and_or_b32 v0, v164, 31, v165
	v_ashrrev_i32_e32 v1, 31, v0
	v_lshlrev_b64 v[0:1], 11, v[0:1]
	v_lshl_add_u64 v[0:1], s[14:15], 0, v[0:1]
	v_lshl_add_u64 v[0:1], v[0:1], 0, v[152:153]
	v_lshlrev_b32_e32 v152, 1, v59
	v_lshl_add_u64 v[0:1], v[0:1], 0, v[152:153]
	v_lshl_add_u64 v[4:5], v[0:1], 0, s[10:11]
	s_mov_b32 s10, 0x2b7c000
	v_add_co_u32_e32 v0, vcc, s10, v0
	v_cvt_pk_bf16_f32 v2, v43, v44
	v_cvt_pk_bf16_f32 v3, v45, v3
	s_nop 1
	v_addc_co_u32_e32 v1, vcc, 0, v1, vcc
	global_store_dwordx2 v[0:1], v[2:3], off offset:768
	v_cvt_pk_bf16_f32 v0, v32, v33
	v_cvt_pk_bf16_f32 v1, v34, v35
	global_store_dwordx2 v[4:5], v[0:1], off offset:16
	v_cvt_pk_bf16_f32 v0, v36, v37
	v_cvt_pk_bf16_f32 v1, v38, v39
	global_store_dwordx2 v[4:5], v[0:1], off offset:32
	v_cvt_pk_bf16_f32 v0, v16, v17
	v_cvt_pk_bf16_f32 v1, v18, v19
	global_store_dwordx2 v[4:5], v[0:1], off offset:48
	v_cvt_pk_bf16_f32 v0, v46, v47
	v_cvt_pk_bf16_f32 v1, v6, v7
	global_store_dwordx2 v[4:5], v[0:1], off offset:64
	v_cvt_pk_bf16_f32 v0, v20, v21
	v_cvt_pk_bf16_f32 v1, v22, v23
	global_store_dwordx2 v[4:5], v[0:1], off offset:80
	v_cvt_pk_bf16_f32 v0, v8, v9
	v_cvt_pk_bf16_f32 v1, v10, v11
	global_store_dwordx2 v[4:5], v[0:1], off offset:96
	v_cvt_pk_bf16_f32 v0, v12, v13
	v_cvt_pk_bf16_f32 v1, v14, v15
	global_store_dwordx2 v[4:5], v[0:1], off offset:112
	s_or_b64 exec, exec, s[8:9]

; DI void attn_pass_da(const bfr* __restrict__ P, int b, int tq_wave, int qcol, int kcol, int vcol, int key0, int nkt, char* smem, f32x16 (&o0)[2], f32x16 (&o1)[2]) {
;     ...
;   for (int kt = 0; kt < nkt; ++kt) {
;     bfr* sK = sbase + (kt & 1) * 9216;
;     bfr* sV = sK + 64 * 72;
;     { int c = gt, row = c >> 3, kc = c & 7; *(u32x4*)(sK + row * KP + kc * 8) = kreg[0]; }
;     for (int i = 0; i < 1; ++i) {
;       int c = gt, row = c >> 3, kc = c & 7;
;       unsigned wds[4] = {vreg[i].x, vreg[i].y, vreg[i].z, vreg[i].w};
; #pragma unroll
;       for (int e = 0; e < 4; ++e) {
;         sV[(kc * 8 + 2 * e) * 72 + (row ^ (kc << 3))] = (bfr)(wds[e] & 0xffffu);
;         sV[(kc * 8 + 2 * e + 1) * 72 + (row ^ (kc << 3))] = (bfr)(wds[e] >> 16);
;       }
;     }
;     __syncthreads();
;     if (kt + 1 < nkt) {
;       const bfr* Pn = Pb + (size_t)(kt + 1) * 64 * PW;
;       { int c = gt, row = c >> 3, kc = c & 7; kreg[0] = *(const u32x4*)(Pn + (size_t)row * PW + kcol + kc * 8); vreg[0] = *(const u32x4*)(Pn + (size_t)row * PW + vcol + kc * 8); }
;     }
;     f32x16 s0[2], s1[2];
; #pragma unroll
;     for (int t2 = 0; t2 < 2; ++t2) {
; #pragma unroll
;       for (int i = 0; i < 16; ++i) { s0[t2][i] = 0.f; s1[t2][i] = 0.f; }
; #pragma unroll
;       for (int ks = 0; ks < 2; ++ks) {
;         bf16x8 a0 = *(const bf16x8*)(sK + (t2 * 32 + r) * KP + ks * 16 + h * 8);
;         bf16x8 a1 = *(const bf16x8*)(sK + (t2 * 32 + r) * KP + 32 + ks * 16 + h * 8);
;         s0[t2] = MFMA32(a0, qf[ks], s0[t2]);
;         s1[t2] = MFMA32(a1, qf[2 + ks], s1[t2]);
;       }
;     }
;     float mx0 = s0[0][0], mx1 = s1[0][0];
; #pragma unroll
;     for (int i = 0; i < 16; ++i) { mx0 = fmaxf(mx0, fmaxf(s0[0][i], s0[1][i])); mx1 = fmaxf(mx1, fmaxf(s1[0][i], s1[1][i])); }
;     mx0 = fmaxf(mx0, __shfl_xor(mx0, 32)); mx1 = fmaxf(mx1, __shfl_xor(mx1, 32));
;     const float mn0 = fmaxf(m0, mx0), mn1 = fmaxf(m1, mx1);
;     const float al0 = __builtin_amdgcn_exp2f(m0 - mn0), al1 = __builtin_amdgcn_exp2f(m1 - mn1);
;     m0 = mn0; m1 = mn1;
;     float ps0 = 0.f, ps1 = 0.f;
; #pragma unroll
;     for (int i = 0; i < 16; ++i) {
;       s0[0][i] = __builtin_amdgcn_exp2f(s0[0][i] - mn0); ps0 += s0[0][i];
;       s0[1][i] = __builtin_amdgcn_exp2f(s0[1][i] - mn0); ps0 += s0[1][i];
;       s1[0][i] = __builtin_amdgcn_exp2f(s1[0][i] - mn1); ps1 += s1[0][i];
.LBB0_421:
	s_bitcmp1_b32 s10, 0
	s_cselect_b32 s11, 0x4800, 0
	s_add_i32 s11, s11, 0
	v_add3_u32 v64, s11, v206, v152
	v_add_u32_e32 v194, s11, v205
	s_waitcnt vmcnt(1)
	ds_write_b128 v64, v[148:151]
	v_add3_u32 v64, s11, v207, v208
	v_add3_u32 v65, s11, v208, v207
	v_add_u32_e32 v100, v194, v204
	s_waitcnt vmcnt(0)
	ds_write_b16 v64, v144 offset:9216
	ds_write_b16_d16_hi v65, v144 offset:9360
	ds_write_b16 v64, v145 offset:9504
	ds_write_b16_d16_hi v65, v145 offset:9648
	ds_write_b16 v64, v146 offset:9792
	ds_write_b16_d16_hi v65, v146 offset:9936
	ds_write_b16 v64, v147 offset:10080
	ds_write_b16_d16_hi v65, v147 offset:10224
	s_waitcnt lgkmcnt(0)
	s_barrier
	global_load_dwordx4 v[148:151], v[158:159], off
	global_load_dwordx4 v[144:147], v[158:159], off offset:512
	ds_read_b128 v[64:67], v100 offset:64
	ds_read_b128 v[68:71], v100
	ds_read_b128 v[96:99], v100 offset:32
	ds_read_b128 v[100:103], v100 offset:96
	s_waitcnt lgkmcnt(2)
	v_mfma_f32_32x32x16_bf16 v[80:95], v[68:71], v[140:143], 0
	v_add_u32_e32 v195, s11, v211
	v_add_u32_e32 v192, v195, v204
	v_mov_b32_e32 v160, v209
	v_mov_b32_e32 v161, v210
	s_add_i32 s10, s10, 1
	v_lshl_add_u64 v[158:159], v[158:159], 0, s[12:13]
	s_cmp_lg_u32 s10, 35
	v_mfma_f32_32x32x16_bf16 v[64:79], v[64:67], v[136:139], 0
	s_waitcnt lgkmcnt(1)
	v_mfma_f32_32x32x16_bf16 v[80:95], v[96:99], v[132:135], v[80:95]
	s_waitcnt lgkmcnt(0)
	v_mfma_f32_32x32x16_bf16 v[64:79], v[100:103], v[128:131], v[64:79]
	ds_read_b128 v[96:99], v192 offset:64
	ds_read_b128 v[100:103], v192
	ds_read_b128 v[212:215], v192 offset:32
	ds_read_b128 v[216:219], v192 offset:96
	s_nop 5
	v_max3_f32 v209, v80, v81, v82
	v_max3_f32 v209, v209, v83, v84
	v_max3_f32 v193, v64, v65, v66
	s_waitcnt lgkmcnt(2)
	v_mfma_f32_32x32x16_bf16 v[112:127], v[100:103], v[140:143], 0
	v_mfma_f32_32x32x16_bf16 v[96:111], v[96:99], v[136:139], 0
	s_waitcnt lgkmcnt(1)
	v_mfma_f32_32x32x16_bf16 v[112:127], v[212:215], v[132:135], v[112:127]
	v_max3_f32 v193, v193, v67, v68
	v_max3_f32 v209, v209, v85, v86
	s_waitcnt lgkmcnt(0)
	v_mfma_f32_32x32x16_bf16 v[96:111], v[216:219], v[128:131], v[96:111]
	v_max3_f32 v193, v193, v69, v70
	v_max3_f32 v209, v209, v87, v88
	v_max3_f32 v193, v193, v71, v72
	v_max3_f32 v209, v209, v89, v90
	v_max3_f32 v193, v193, v73, v74
	v_max3_f32 v209, v209, v91, v92
	v_max3_f32 v193, v193, v75, v76
	v_max3_f32 v209, v209, v93, v94
	v_max3_f32 v193, v193, v77, v78
	v_max3_f32 v209, v209, v95, v112
	v_max3_f32 v209, v209, v113, v114
	v_max3_f32 v209, v209, v115, v116
	v_max3_f32 v209, v209, v117, v118
	v_max3_f32 v209, v209, v119, v120
	v_max3_f32 v209, v209, v121, v122
	v_max3_f32 v209, v209, v123, v124
	v_max3_f32 v209, v209, v125, v126
	v_max_f32_e32 v192, v209, v127
	v_max3_f32 v193, v193, v79, v96
	v_max3_f32 v193, v193, v97, v98
	v_max3_f32 v193, v193, v99, v100
	v_max3_f32 v193, v193, v101, v102
	v_max3_f32 v193, v193, v103, v104
	v_max3_f32 v193, v193, v105, v106
	v_max3_f32 v193, v193, v107, v108
	v_max3_f32 v193, v193, v109, v110
	v_max_f32_e32 v193, v193, v111
	ds_bpermute_b32 v210, v166, v193
	ds_bpermute_b32 v209, v166, v192
	s_waitcnt lgkmcnt(1)
	v_max3_f32 v210, v161, v193, v210
	s_waitcnt lgkmcnt(0)
	v_max3_f32 v209, v160, v192, v209
	v_sub_f32_e32 v161, v161, v210
	v_sub_f32_e32 v160, v160, v209
	v_exp_f32_e32 v161, v161
	v_exp_f32_e32 v160, v160
	v_pk_add_f32 v[64:65], v[64:65], v[210:211] op_sel_hi:[1,0] neg_lo:[0,1] neg_hi:[0,1]
	v_pk_add_f32 v[80:81], v[80:81], v[208:209] op_sel:[0,1] op_sel_hi:[1,1] neg_lo:[0,1] neg_hi:[0,1]
	v_exp_f32_e32 v193, v64
	v_pk_add_f32 v[96:97], v[96:97], v[210:211] op_sel_hi:[1,0] neg_lo:[0,1] neg_hi:[0,1]
	v_exp_f32_e32 v192, v80
	v_pk_mul_f32 v[62:63], v[62:63], v[160:161] op_sel_hi:[1,0]
	v_pk_add_f32 v[112:113], v[112:113], v[208:209] op_sel:[0,1] op_sel_hi:[1,1] neg_lo:[0,1] neg_hi:[0,1]
	v_exp_f32_e32 v213, v96
	v_exp_f32_e32 v212, v112
	v_pk_mul_f32 v[60:61], v[60:61], v[160:161] op_sel_hi:[1,0]
	v_exp_f32_e32 v80, v81
	v_exp_f32_e32 v96, v113
	v_pk_mul_f32 v[58:59], v[58:59], v[160:161] op_sel_hi:[1,0]
	v_exp_f32_e32 v81, v65
	v_exp_f32_e32 v97, v97
	v_pk_mul_f32 v[56:57], v[56:57], v[160:161] op_sel_hi:[1,0]
	v_pk_add_f32 v[82:83], v[82:83], v[208:209] op_sel:[0,1] op_sel_hi:[1,1] neg_lo:[0,1] neg_hi:[0,1]
	v_exp_f32_e32 v112, v82
	v_pk_add_f32 v[114:115], v[114:115], v[208:209] op_sel:[0,1] op_sel_hi:[1,1] neg_lo:[0,1] neg_hi:[0,1]
	v_exp_f32_e32 v214, v114
	v_pk_mul_f32 v[54:55], v[54:55], v[160:161] op_sel_hi:[1,0]
	v_pk_add_f32 v[66:67], v[66:67], v[210:211] op_sel_hi:[1,0] neg_lo:[0,1] neg_hi:[0,1]
	v_exp_f32_e32 v113, v66
	v_pk_add_f32 v[98:99], v[98:99], v[210:211] op_sel_hi:[1,0] neg_lo:[0,1] neg_hi:[0,1]
	v_exp_f32_e32 v215, v98
	v_pk_mul_f32 v[52:53], v[52:53], v[160:161] op_sel_hi:[1,0]
	v_exp_f32_e32 v82, v83
	v_exp_f32_e32 v98, v115
	v_pk_mul_f32 v[50:51], v[50:51], v[160:161] op_sel_hi:[1,0]
	v_exp_f32_e32 v83, v67
	v_exp_f32_e32 v99, v99
	v_pk_mul_f32 v[48:49], v[48:49], v[160:161] op_sel_hi:[1,0]
	v_pk_add_f32 v[84:85], v[84:85], v[208:209] op_sel:[0,1] op_sel_hi:[1,1] neg_lo:[0,1] neg_hi:[0,1]
	v_exp_f32_e32 v114, v84
	v_pk_add_f32 v[116:117], v[116:117], v[208:209] op_sel:[0,1] op_sel_hi:[1,1] neg_lo:[0,1] neg_hi:[0,1]
	v_exp_f32_e32 v216, v116
	v_pk_mul_f32 v[30:31], v[30:31], v[160:161] op_sel_hi:[1,0]
	v_pk_add_f32 v[68:69], v[68:69], v[210:211] op_sel_hi:[1,0] neg_lo:[0,1] neg_hi:[0,1]
	v_exp_f32_e32 v115, v68
	v_pk_add_f32 v[100:101], v[100:101], v[210:211] op_sel_hi:[1,0] neg_lo:[0,1] neg_hi:[0,1]
	v_exp_f32_e32 v217, v100
	v_pk_mul_f32 v[28:29], v[28:29], v[160:161] op_sel_hi:[1,0]
	v_exp_f32_e32 v84, v85
	v_exp_f32_e32 v100, v117
; DI unsigned pack2(float a, float b) { unsigned r; asm volatile("v_cvt_pk_bf16_f32 %0, %1, %2" : "=v"(r) : "v"(a), "v"(b)); return r; }
; DI void attn_pass_da(const bfr* __restrict__ P, int b, int tq_wave, int qcol, int kcol, int vcol, int key0, int nkt, char* smem, f32x16 (&o0)[2], f32x16 (&o1)[2]) {
;     ...
;     const float mn0 = fmaxf(m0, mx0), mn1 = fmaxf(m1, mx1);
;     const float al0 = __builtin_amdgcn_exp2f(m0 - mn0), al1 = __builtin_amdgcn_exp2f(m1 - mn1);
;     m0 = mn0; m1 = mn1;
;     float ps0 = 0.f, ps1 = 0.f;
; #pragma unroll
;     for (int i = 0; i < 16; ++i) {
;       s0[0][i] = __builtin_amdgcn_exp2f(s0[0][i] - mn0); ps0 += s0[0][i];
;       s0[1][i] = __builtin_amdgcn_exp2f(s0[1][i] - mn0); ps0 += s0[1][i];
;       s1[0][i] = __builtin_amdgcn_exp2f(s1[0][i] - mn1); ps1 += s1[0][i];
;       s1[1][i] = __builtin_amdgcn_exp2f(s1[1][i] - mn1); ps1 += s1[1][i];
;     }
;     l0 = l0 * al0 + ps0; l1 = l1 * al1 + ps1;
; #pragma unroll
;     for (int i = 0; i < 16; ++i) { acc0[0][i] *= al0; acc0[1][i] *= al0; acc1[0][i] *= al1; acc1[1][i] *= al1; }
; #pragma unroll
;     for (int t2 = 0; t2 < 2; ++t2)
; #pragma unroll
;       for (int j = 0; j < 2; ++j) {
;         u32x4 pk0, pk1;
;         pk0.x = pack2(s0[t2][8 * j + 0], s0[t2][8 * j + 1]); pk0.y = pack2(s0[t2][8 * j + 2], s0[t2][8 * j + 3]);
;         pk0.z = pack2(s0[t2][8 * j + 4], s0[t2][8 * j + 5]); pk0.w = pack2(s0[t2][8 * j + 6], s0[t2][8 * j + 7]);
;         pk1.x = pack2(s1[t2][8 * j + 0], s1[t2][8 * j + 1]); pk1.y = pack2(s1[t2][8 * j + 2], s1[t2][8 * j + 3]);
;         pk1.z = pack2(s1[t2][8 * j + 4], s1[t2][8 * j + 5]); pk1.w = pack2(s1[t2][8 * j + 6], s1[t2][8 * j + 7]);
;         const bf16x8 pf0 = __builtin_bit_cast(bf16x8, pk0), pf1 = __builtin_bit_cast(bf16x8, pk1);
; #pragma unroll
;         for (int dt = 0; dt < 2; ++dt) {
;           const int vsw = (((dt * 32 + r) >> 3) & 7) << 3;
;           const bfr* vrow = sV + (dt * 32 + r) * 72;
;           s16x4 lo = *(const s16x4*)(vrow + ((t2 * 32 + 16 * j + 4 * h) ^ vsw));
;           s16x4 hi = *(const s16x4*)(vrow + ((t2 * 32 + 16 * j + 4 * h + 8) ^ vsw));
;           bf16x8 vf = __builtin_shufflevector(lo, hi, 0, 1, 2, 3, 4, 5, 6, 7);
	v_pk_mul_f32 v[26:27], v[26:27], v[160:161] op_sel_hi:[1,0]
	v_exp_f32_e32 v85, v69
	v_exp_f32_e32 v101, v101
	v_pk_mul_f32 v[24:25], v[24:25], v[160:161] op_sel_hi:[1,0]
	v_pk_add_f32 v[86:87], v[86:87], v[208:209] op_sel:[0,1] op_sel_hi:[1,1] neg_lo:[0,1] neg_hi:[0,1]
	v_exp_f32_e32 v116, v86
	v_pk_add_f32 v[118:119], v[118:119], v[208:209] op_sel:[0,1] op_sel_hi:[1,1] neg_lo:[0,1] neg_hi:[0,1]
	v_exp_f32_e32 v218, v118
	v_pk_mul_f32 v[22:23], v[22:23], v[160:161] op_sel_hi:[1,0]
	v_pk_add_f32 v[70:71], v[70:71], v[210:211] op_sel_hi:[1,0] neg_lo:[0,1] neg_hi:[0,1]
	v_exp_f32_e32 v117, v70
	v_pk_add_f32 v[102:103], v[102:103], v[210:211] op_sel_hi:[1,0] neg_lo:[0,1] neg_hi:[0,1]
	v_exp_f32_e32 v219, v102
	v_pk_mul_f32 v[20:21], v[20:21], v[160:161] op_sel_hi:[1,0]
	v_exp_f32_e32 v70, v87
	v_exp_f32_e32 v86, v119
	v_pk_mul_f32 v[46:47], v[46:47], v[160:161] op_sel:[0,1] op_sel_hi:[1,1]
	v_exp_f32_e32 v71, v71
	v_exp_f32_e32 v87, v103
	v_pk_mul_f32 v[44:45], v[44:45], v[160:161] op_sel:[0,1] op_sel_hi:[1,1]
	v_pk_add_f32 v[88:89], v[88:89], v[208:209] op_sel:[0,1] op_sel_hi:[1,1] neg_lo:[0,1] neg_hi:[0,1]
	v_exp_f32_e32 v102, v88
	v_pk_add_f32 v[120:121], v[120:121], v[208:209] op_sel:[0,1] op_sel_hi:[1,1] neg_lo:[0,1] neg_hi:[0,1]
	v_exp_f32_e32 v118, v120
	v_pk_mul_f32 v[42:43], v[42:43], v[160:161] op_sel:[0,1] op_sel_hi:[1,1]
	v_pk_add_f32 v[72:73], v[72:73], v[210:211] op_sel_hi:[1,0] neg_lo:[0,1] neg_hi:[0,1]
	v_exp_f32_e32 v103, v72
	v_pk_add_f32 v[104:105], v[104:105], v[210:211] op_sel_hi:[1,0] neg_lo:[0,1] neg_hi:[0,1]
	v_exp_f32_e32 v119, v104
	v_pk_mul_f32 v[40:41], v[40:41], v[160:161] op_sel:[0,1] op_sel_hi:[1,1]
	v_exp_f32_e32 v88, v89
	v_exp_f32_e32 v104, v121
	v_pk_mul_f32 v[38:39], v[38:39], v[160:161] op_sel:[0,1] op_sel_hi:[1,1]
	v_exp_f32_e32 v89, v73
	v_exp_f32_e32 v105, v105
	v_pk_mul_f32 v[36:37], v[36:37], v[160:161] op_sel:[0,1] op_sel_hi:[1,1]
	v_pk_add_f32 v[90:91], v[90:91], v[208:209] op_sel:[0,1] op_sel_hi:[1,1] neg_lo:[0,1] neg_hi:[0,1]
	v_exp_f32_e32 v120, v90
	v_pk_add_f32 v[122:123], v[122:123], v[208:209] op_sel:[0,1] op_sel_hi:[1,1] neg_lo:[0,1] neg_hi:[0,1]
	v_exp_f32_e32 v220, v122
	v_pk_mul_f32 v[34:35], v[34:35], v[160:161] op_sel:[0,1] op_sel_hi:[1,1]
	v_pk_add_f32 v[74:75], v[74:75], v[210:211] op_sel_hi:[1,0] neg_lo:[0,1] neg_hi:[0,1]
	v_exp_f32_e32 v121, v74
	v_pk_add_f32 v[106:107], v[106:107], v[210:211] op_sel_hi:[1,0] neg_lo:[0,1] neg_hi:[0,1]
	v_exp_f32_e32 v221, v106
	v_pk_mul_f32 v[32:33], v[32:33], v[160:161] op_sel:[0,1] op_sel_hi:[1,1]
	v_exp_f32_e32 v90, v91
	v_exp_f32_e32 v106, v123
	v_pk_mul_f32 v[14:15], v[14:15], v[160:161] op_sel:[0,1] op_sel_hi:[1,1]
	v_exp_f32_e32 v91, v75
	v_exp_f32_e32 v107, v107
	v_pk_mul_f32 v[12:13], v[12:13], v[160:161] op_sel:[0,1] op_sel_hi:[1,1]
	v_pk_add_f32 v[92:93], v[92:93], v[208:209] op_sel:[0,1] op_sel_hi:[1,1] neg_lo:[0,1] neg_hi:[0,1]
	v_exp_f32_e32 v122, v92
	v_pk_add_f32 v[124:125], v[124:125], v[208:209] op_sel:[0,1] op_sel_hi:[1,1] neg_lo:[0,1] neg_hi:[0,1]
	v_exp_f32_e32 v222, v124
	v_pk_mul_f32 v[10:11], v[10:11], v[160:161] op_sel:[0,1] op_sel_hi:[1,1]
	v_pk_add_f32 v[76:77], v[76:77], v[210:211] op_sel_hi:[1,0] neg_lo:[0,1] neg_hi:[0,1]
	v_exp_f32_e32 v123, v76
	v_pk_add_f32 v[108:109], v[108:109], v[210:211] op_sel_hi:[1,0] neg_lo:[0,1] neg_hi:[0,1]
	v_exp_f32_e32 v223, v108
	v_pk_mul_f32 v[8:9], v[8:9], v[160:161] op_sel:[0,1] op_sel_hi:[1,1]
	v_exp_f32_e32 v92, v93
	v_exp_f32_e32 v108, v125
	v_pk_mul_f32 v[6:7], v[6:7], v[160:161] op_sel:[0,1] op_sel_hi:[1,1]
	v_exp_f32_e32 v93, v77
	v_exp_f32_e32 v109, v109
	v_pk_mul_f32 v[4:5], v[4:5], v[160:161] op_sel:[0,1] op_sel_hi:[1,1]
	v_pk_add_f32 v[94:95], v[94:95], v[208:209] op_sel:[0,1] op_sel_hi:[1,1] neg_lo:[0,1] neg_hi:[0,1]
	v_exp_f32_e32 v124, v94
	v_pk_add_f32 v[126:127], v[126:127], v[208:209] op_sel:[0,1] op_sel_hi:[1,1] neg_lo:[0,1] neg_hi:[0,1]
	v_exp_f32_e32 v224, v126
	v_pk_mul_f32 v[2:3], v[2:3], v[160:161] op_sel:[0,1] op_sel_hi:[1,1]
	v_pk_add_f32 v[78:79], v[78:79], v[210:211] op_sel_hi:[1,0] neg_lo:[0,1] neg_hi:[0,1]
	v_exp_f32_e32 v125, v78
	v_pk_add_f32 v[110:111], v[110:111], v[210:211] op_sel_hi:[1,0] neg_lo:[0,1] neg_hi:[0,1]
	v_exp_f32_e32 v225, v110
	v_pk_mul_f32 v[0:1], v[0:1], v[160:161] op_sel:[0,1] op_sel_hi:[1,1]
	v_exp_f32_e32 v94, v95
	v_exp_f32_e32 v110, v127
	v_pk_mul_f32 v[18:19], v[18:19], v[160:161] op_sel_hi:[1,0]
	v_exp_f32_e32 v95, v79
	v_exp_f32_e32 v111, v111
	v_pk_mul_f32 v[16:17], v[16:17], v[160:161] op_sel_hi:[1,0]
	v_pk_add_f32 v[64:65], v[192:193], 0 op_sel_hi:[1,0]
	v_pk_add_f32 v[64:65], v[212:213], v[64:65]
	v_pk_add_f32 v[64:65], v[80:81], v[64:65]
	v_lshl_add_u32 v74, v180, 1, v194
	v_pk_add_f32 v[64:65], v[96:97], v[64:65]
	v_lshl_add_u32 v76, v179, 1, v195
	v_pk_add_f32 v[64:65], v[112:113], v[64:65]
	v_lshl_add_u32 v78, v178, 1, v195
	v_pk_add_f32 v[64:65], v[214:215], v[64:65]
	v_pk_add_f32 v[64:65], v[82:83], v[64:65]
	v_pk_add_f32 v[64:65], v[98:99], v[64:65]
	v_pk_add_f32 v[64:65], v[114:115], v[64:65]
	v_pk_add_f32 v[64:65], v[216:217], v[64:65]
	v_pk_add_f32 v[64:65], v[84:85], v[64:65]
	v_pk_add_f32 v[64:65], v[100:101], v[64:65]
	v_pk_add_f32 v[64:65], v[116:117], v[64:65]
	v_pk_add_f32 v[64:65], v[218:219], v[64:65]
	v_pk_add_f32 v[64:65], v[70:71], v[64:65]
	v_pk_add_f32 v[64:65], v[86:87], v[64:65]
	v_pk_add_f32 v[64:65], v[102:103], v[64:65]
	v_pk_add_f32 v[64:65], v[118:119], v[64:65]
	v_pk_add_f32 v[64:65], v[88:89], v[64:65]
	v_pk_add_f32 v[64:65], v[104:105], v[64:65]
	v_pk_add_f32 v[64:65], v[120:121], v[64:65]
	v_pk_add_f32 v[126:127], v[220:221], v[64:65]
	v_cvt_pk_bf16_f32 v64, v192, v80
	v_cvt_pk_bf16_f32 v65, v112, v82
	v_lshl_add_u32 v112, v181, 1, v194
	v_cvt_pk_bf16_f32 v66, v114, v84
	v_cvt_pk_bf16_f32 v67, v116, v70
	v_cvt_pk_bf16_f32 v68, v193, v81
	v_cvt_pk_bf16_f32 v69, v113, v83
	v_cvt_pk_bf16_f32 v70, v115, v85
	v_cvt_pk_bf16_f32 v71, v117, v71
	ds_read_b64 v[72:73], v112 offset:9216
	ds_read_b64 v[74:75], v74 offset:9216
	ds_read_b64 v[76:77], v76 offset:9216
	ds_read_b64 v[78:79], v78 offset:9216
	v_pk_add_f32 v[82:83], v[90:91], v[126:127]
	s_waitcnt lgkmcnt(2)
; DI void attn_pass_da(const bfr* __restrict__ P, int b, int tq_wave, int qcol, int kcol, int vcol, int key0, int nkt, char* smem, f32x16 (&o0)[2], f32x16 (&o1)[2]) {
;     ...
;   for (int kt = 0; kt < nkt; ++kt) {
;     bfr* sK = sbase + (kt & 1) * 9216;
;     bfr* sV = sK + 64 * 72;
;     { int c = gt, row = c >> 3, kc = c & 7; *(u32x4*)(sK + row * KP + kc * 8) = kreg[0]; }
;     for (int i = 0; i < 1; ++i) {
;       int c = gt, row = c >> 3, kc = c & 7;
;       unsigned wds[4] = {vreg[i].x, vreg[i].y, vreg[i].z, vreg[i].w};
; #pragma unroll
;       for (int e = 0; e < 4; ++e) {
;         sV[(kc * 8 + 2 * e) * 72 + (row ^ (kc << 3))] = (bfr)(wds[e] & 0xffffu);
;         sV[(kc * 8 + 2 * e + 1) * 72 + (row ^ (kc << 3))] = (bfr)(wds[e] >> 16);
;       }
;     }
;     __syncthreads();
;     if (kt + 1 < nkt) {
;       const bfr* Pn = Pb + (size_t)(kt + 1) * 64 * PW;
;       { int c = gt, row = c >> 3, kc = c & 7; kreg[0] = *(const u32x4*)(Pn + (size_t)row * PW + kcol + kc * 8); vreg[0] = *(const u32x4*)(Pn + (size_t)row * PW + vcol + kc * 8); }
;     }
;     f32x16 s0[2], s1[2];
; #pragma unroll
;     for (int t2 = 0; t2 < 2; ++t2) {
;     ...
; #pragma unroll
;     for (int t2 = 0; t2 < 2; ++t2)
; #pragma unroll
;       for (int j = 0; j < 2; ++j) {
;         u32x4 pk0, pk1;
;         pk0.x = pack2(s0[t2][8 * j + 0], s0[t2][8 * j + 1]); pk0.y = pack2(s0[t2][8 * j + 2], s0[t2][8 * j + 3]);
;         pk0.z = pack2(s0[t2][8 * j + 4], s0[t2][8 * j + 5]); pk0.w = pack2(s0[t2][8 * j + 6], s0[t2][8 * j + 7]);
;         pk1.x = pack2(s1[t2][8 * j + 0], s1[t2][8 * j + 1]); pk1.y = pack2(s1[t2][8 * j + 2], s1[t2][8 * j + 3]);
;         pk1.z = pack2(s1[t2][8 * j + 4], s1[t2][8 * j + 5]); pk1.w = pack2(s1[t2][8 * j + 6], s1[t2][8 * j + 7]);
;         const bf16x8 pf0 = __builtin_bit_cast(bf16x8, pk0), pf1 = __builtin_bit_cast(bf16x8, pk1);
; #pragma unroll
;         for (int dt = 0; dt < 2; ++dt) {
;           const int vsw = (((dt * 32 + r) >> 3) & 7) << 3;
;           const bfr* vrow = sV + (dt * 32 + r) * 72;
;           s16x4 lo = *(const s16x4*)(vrow + ((t2 * 32 + 16 * j + 4 * h) ^ vsw));
;           s16x4 hi = *(const s16x4*)(vrow + ((t2 * 32 + 16 * j + 4 * h + 8) ^ vsw));
;           bf16x8 vf = __builtin_shufflevector(lo, hi, 0, 1, 2, 3, 4, 5, 6, 7);
;           acc0[dt] = MFMA32(vf, pf0, acc0[dt]);
;           acc1[dt] = MFMA32(vf, pf1, acc1[dt]);
;         }
;       }
	v_mfma_f32_32x32x16_bf16 v[48:63], v[72:75], v[64:67], v[48:63]
	v_add_f32_e64 v82, v106, v82
	v_add_f32_e64 v83, v107, v83
	v_cvt_pk_bf16_f32 v80, v102, v88
	v_lshl_add_u32 v88, v177, 1, v194
	v_add_f32_e64 v82, v122, v82
	v_add_f32_e64 v83, v123, v83
	v_pk_add_f32 v[82:83], v[222:223], v[82:83]
	v_pk_add_f32 v[82:83], v[92:93], v[82:83]
	v_mfma_f32_32x32x16_bf16 v[32:47], v[72:75], v[68:71], v[32:47]
	v_add_f32_e64 v82, v108, v82
	v_add_f32_e64 v83, v109, v83
	v_cvt_pk_bf16_f32 v81, v120, v90
	v_lshl_add_u32 v102, v176, 1, v194
	v_add_f32_e64 v82, v124, v82
	v_add_f32_e64 v83, v125, v83
	v_lshl_add_u32 v113, v175, 1, v195
	v_pk_add_f32 v[82:83], v[224:225], v[82:83]
	v_lshl_add_u32 v114, v174, 1, v195
	v_pk_add_f32 v[82:83], v[94:95], v[82:83]
	s_waitcnt lgkmcnt(0)
	v_mfma_f32_32x32x16_bf16 v[16:31], v[76:79], v[64:67], v[16:31]
	v_add_f32_e64 v84, v110, v82
	v_add_f32_e64 v85, v111, v83
	v_cvt_pk_bf16_f32 v82, v122, v92
	v_cvt_pk_bf16_f32 v83, v124, v94
	v_cvt_pk_bf16_f32 v64, v103, v89
	v_cvt_pk_bf16_f32 v65, v121, v91
	v_cvt_pk_bf16_f32 v66, v123, v93
	v_cvt_pk_bf16_f32 v67, v125, v95
	v_mfma_f32_32x32x16_bf16 v[0:15], v[76:79], v[68:71], v[0:15]
	ds_read_b64 v[68:69], v88 offset:9216
	ds_read_b64 v[70:71], v102 offset:9216
	v_lshl_add_u32 v115, v173, 1, v194
	v_lshl_add_u32 v116, v172, 1, v195
	v_lshl_add_u32 v117, v171, 1, v195
	v_lshl_add_u32 v120, v169, 1, v194
	v_lshl_add_u32 v192, v170, 1, v194
	v_lshl_add_u32 v193, v168, 1, v195
	s_waitcnt lgkmcnt(0)
	v_mfma_f32_32x32x16_bf16 v[48:63], v[68:71], v[80:83], v[48:63]
	v_lshl_add_u32 v194, v167, 1, v195
	v_fma_f32 v156, v156, v160, v84
	v_fma_f32 v157, v157, v161, v85
	v_mfma_f32_32x32x16_bf16 v[32:47], v[68:71], v[64:67], v[32:47]
	ds_read_b64 v[68:69], v113 offset:9216
	ds_read_b64 v[70:71], v114 offset:9216
	s_waitcnt lgkmcnt(0)
	v_mfma_f32_32x32x16_bf16 v[16:31], v[68:71], v[80:83], v[16:31]
	v_mfma_f32_32x32x16_bf16 v[0:15], v[68:71], v[64:67], v[0:15]
	v_cvt_pk_bf16_f32 v64, v212, v96
	v_cvt_pk_bf16_f32 v65, v214, v98
	v_cvt_pk_bf16_f32 v66, v216, v100
	v_cvt_pk_bf16_f32 v67, v218, v86
	v_cvt_pk_bf16_f32 v68, v213, v97
	v_cvt_pk_bf16_f32 v69, v215, v99
	v_cvt_pk_bf16_f32 v70, v217, v101
	v_cvt_pk_bf16_f32 v71, v219, v87
	ds_read_b64 v[72:73], v112 offset:9280
	ds_read_b64 v[74:75], v115 offset:9216
	s_waitcnt lgkmcnt(0)
	v_mfma_f32_32x32x16_bf16 v[48:63], v[72:75], v[64:67], v[48:63]
	v_mfma_f32_32x32x16_bf16 v[32:47], v[72:75], v[68:71], v[32:47]
	ds_read_b64 v[72:73], v116 offset:9216
	ds_read_b64 v[74:75], v117 offset:9216
	s_waitcnt lgkmcnt(0)
	v_mfma_f32_32x32x16_bf16 v[16:31], v[72:75], v[64:67], v[16:31]
	v_cvt_pk_bf16_f32 v64, v118, v104
	v_cvt_pk_bf16_f32 v65, v220, v106
	v_cvt_pk_bf16_f32 v66, v222, v108
	v_cvt_pk_bf16_f32 v67, v224, v110
	v_mfma_f32_32x32x16_bf16 v[0:15], v[72:75], v[68:71], v[0:15]
	v_cvt_pk_bf16_f32 v68, v119, v105
	v_cvt_pk_bf16_f32 v69, v221, v107
	v_cvt_pk_bf16_f32 v70, v223, v109
	v_cvt_pk_bf16_f32 v71, v225, v111
	ds_read_b64 v[72:73], v120 offset:9216
	ds_read_b64 v[74:75], v192 offset:9216
	s_waitcnt lgkmcnt(0)
	v_mfma_f32_32x32x16_bf16 v[48:63], v[72:75], v[64:67], v[48:63]
	v_mfma_f32_32x32x16_bf16 v[32:47], v[72:75], v[68:71], v[32:47]
	ds_read_b64 v[72:73], v193 offset:9216
	ds_read_b64 v[74:75], v194 offset:9216
	s_waitcnt lgkmcnt(0)
	v_mfma_f32_32x32x16_bf16 v[16:31], v[72:75], v[64:67], v[16:31]
	v_mfma_f32_32x32x16_bf16 v[0:15], v[72:75], v[68:71], v[0:15]
	s_cbranch_scc1 .LBB0_421
	v_add3_u32 v64, 0, v206, v152
	s_waitcnt vmcnt(1)
	ds_write_b128 v64, v[148:151] offset:18432
	v_add3_u32 v64, 0, v207, v208
	v_add3_u32 v65, 0, v208, v207
	s_waitcnt vmcnt(0)
	ds_write_b16 v64, v144 offset:27648
	ds_write_b16_d16_hi v65, v144 offset:27792
	ds_write_b16 v64, v145 offset:27936
	ds_write_b16_d16_hi v65, v145 offset:28080
	ds_write_b16 v64, v146 offset:28224
	ds_write_b16_d16_hi v65, v146 offset:28368
	ds_write_b16 v64, v147 offset:28512
	ds_write_b16_d16_hi v65, v147 offset:28656
	v_add_u32_e32 v144, 0, v205
	v_add_u32_e32 v102, v144, v204
	s_waitcnt lgkmcnt(0)
	s_barrier
	ds_read_b128 v[64:67], v102 offset:18432
	ds_read_b128 v[96:99], v102 offset:18464
	s_waitcnt lgkmcnt(1)
	v_mfma_f32_32x32x16_bf16 v[64:79], v[64:67], v[140:143], 0
	ds_read_b128 v[80:83], v102 offset:18496
	v_readlane_b32 s10, v203, 16
	v_readlane_b32 s11, v203, 48
	v_add_u32_e32 v145, 0x1200, v144
	v_mov_b32_e32 v100, s10
	v_mov_b32_e32 v101, s11
	v_pk_add_f32 v[100:101], s[8:9], v[100:101]
	s_mov_b32 s10, 0x3fb8aa3b
	v_add_f32_e32 v146, v100, v101
	v_mul_f32_e32 v104, 0x3fb8aa3b, v146
	v_fma_f32 v105, v146, s10, -v104
	v_rndne_f32_e32 v106, v104
	s_waitcnt lgkmcnt(1)
	v_mfma_f32_32x32x16_bf16 v[64:79], v[96:99], v[132:135], v[64:79]
	v_fmac_f32_e32 v105, 0x32a5705f, v146
	v_sub_f32_e32 v96, v104, v106
	v_add_u32_e32 v147, v145, v204
	v_add_f32_e32 v104, v96, v105
	ds_read_b128 v[96:99], v147 offset:18432
	ds_read_b128 v[100:103], v102 offset:18528
	ds_read_b128 v[112:115], v147 offset:18496
	s_waitcnt lgkmcnt(3)
	v_mfma_f32_32x32x16_bf16 v[80:95], v[80:83], v[136:139], 0
	v_readlane_b32 s8, v202, 16
	v_readlane_b32 s9, v202, 48
	s_mov_b32 s11, 0xc2ce8ed0
	v_mov_b32_e32 v116, s8
	v_mov_b32_e32 v117, s9
	v_pk_add_f32 v[116:117], s[6:7], v[116:117]
	v_cmp_ngt_f32_e32 vcc, s11, v146
	s_waitcnt lgkmcnt(1)
	v_mfma_f32_32x32x16_bf16 v[80:95], v[100:103], v[128:131], v[80:95]
	v_exp_f32_e32 v100, v104
	v_cvt_i32_f32_e32 v101, v106
	v_add_f32_e32 v149, v116, v117
	v_mul_f32_e32 v150, 0x3fb8aa3b, v149
	v_rndne_f32_e32 v151, v150
	v_ldexp_f32 v148, v100, v101
	s_mov_b32 s6, 0x42b17218
	s_waitcnt lgkmcnt(0)
; #define MFMA32(a, b, c) __builtin_amdgcn_mfma_f32_32x32x16_bf16((a), (b), (c), 0, 0, 0)
; DI void attn_pass_da(const bfr* __restrict__ P, int b, int tq_wave, int qcol, int kcol, int vcol, int key0, int nkt, char* smem, f32x16 (&o0)[2], f32x16 (&o1)[2]) {
;     ...
;     f32x16 s0[2], s1[2];
; #pragma unroll
;     for (int t2 = 0; t2 < 2; ++t2) {
; #pragma unroll
;       for (int i = 0; i < 16; ++i) { s0[t2][i] = 0.f; s1[t2][i] = 0.f; }
; #pragma unroll
;       for (int ks = 0; ks < 2; ++ks) {
;         bf16x8 a0 = *(const bf16x8*)(sK + (t2 * 32 + r) * KP + ks * 16 + h * 8);
;         bf16x8 a1 = *(const bf16x8*)(sK + (t2 * 32 + r) * KP + 32 + ks * 16 + h * 8);
;         s0[t2] = MFMA32(a0, qf[ks], s0[t2]);
;         s1[t2] = MFMA32(a1, qf[2 + ks], s1[t2]);
;       }
;     }
;     float mx0 = s0[0][0], mx1 = s1[0][0];
; #pragma unroll
;     for (int i = 0; i < 16; ++i) { mx0 = fmaxf(mx0, fmaxf(s0[0][i], s0[1][i])); mx1 = fmaxf(mx1, fmaxf(s1[0][i], s1[1][i])); }
;     mx0 = fmaxf(mx0, __shfl_xor(mx0, 32)); mx1 = fmaxf(mx1, __shfl_xor(mx1, 32));
;     const float mn0 = fmaxf(m0, mx0), mn1 = fmaxf(m1, mx1);
; DN void da_item(const Params& p, int l, int b, int hd, int tq0, int key0, int nkt, char* smem) {
;     ...
;   d01 = wave_sum(d01); d23 = wave_sum(d23);
;   float lam_init = 0.8f - 0.6f * expf(-0.3f * (float)l);
;   float lam = expf(d01) - expf(d23) + lam_init;
	v_mfma_f32_32x32x16_bf16 v[112:127], v[112:115], v[136:139], 0
	v_fma_f32 v136, v149, s10, -v150
	v_fmac_f32_e32 v136, 0x32a5705f, v149
	v_sub_f32_e32 v137, v150, v151
	v_add_f32_e32 v136, v137, v136
	v_exp_f32_e32 v150, v136
	ds_read_b128 v[136:139], v147 offset:18528
	v_readlane_b32 s8, v253, 28
	v_mfma_f32_32x32x16_bf16 v[96:111], v[96:99], v[140:143], 0
	ds_read_b128 v[140:143], v147 offset:18464
	v_readlane_b32 s9, v253, 29
	s_waitcnt lgkmcnt(0)
	v_mfma_f32_32x32x16_bf16 v[96:111], v[140:143], v[132:135], v[96:111]
	v_max_f32_e32 v134, v82, v82
	v_max_f32_e32 v135, v67, v67
	v_cvt_i32_f32_e32 v132, v151
	v_cndmask_b32_e32 v133, 0, v148, vcc
	v_cmp_nlt_f32_e32 vcc, s6, v146
	v_ldexp_f32 v132, v150, v132
	v_mfma_f32_32x32x16_bf16 v[112:127], v[136:139], v[128:131], v[112:127]
	s_nop 4
	v_max_f32_e32 v128, v97, v97
	v_max_f32_e32 v129, v65, v65
	v_max_f32_e32 v128, v129, v128
	v_max_f32_e32 v130, v81, v81
	v_max_f32_e32 v131, v66, v66
	v_max3_f32 v128, v64, v96, v128
	v_cndmask_b32_e32 v133, v201, v133, vcc
	v_max_f32_e32 v129, v113, v113
	v_max_f32_e32 v129, v130, v129
	v_max_f32_e32 v130, v98, v98
	v_max_f32_e32 v130, v131, v130
	v_max_f32_e32 v131, v114, v114
	v_max_f32_e32 v131, v134, v131
	v_max_f32_e32 v134, v99, v99
	v_max_f32_e32 v134, v135, v134
	v_max3_f32 v128, v128, v130, v134
	v_max_f32_e32 v130, v115, v115
	v_max_f32_e32 v134, v83, v83
	v_max3_f32 v129, v80, v112, v129
	v_max_f32_e32 v130, v134, v130
	v_max3_f32 v129, v129, v131, v130
	v_max_f32_e32 v130, v100, v100
	v_max_f32_e32 v131, v68, v68
	v_max_f32_e32 v130, v131, v130
	v_max_f32_e32 v131, v116, v116
	v_max_f32_e32 v134, v84, v84
	v_max_f32_e32 v131, v134, v131
	v_max_f32_e32 v134, v101, v101
	v_max_f32_e32 v135, v69, v69
	v_max_f32_e32 v134, v135, v134
	v_max3_f32 v128, v128, v130, v134
	v_max_f32_e32 v130, v117, v117
	v_max_f32_e32 v134, v85, v85
	v_max_f32_e32 v130, v134, v130
	v_max3_f32 v129, v129, v131, v130
	v_max_f32_e32 v130, v102, v102
	v_max_f32_e32 v131, v70, v70
	v_max_f32_e32 v130, v131, v130
	v_max_f32_e32 v131, v118, v118
	v_max_f32_e32 v134, v86, v86
	v_max_f32_e32 v131, v134, v131
	v_max_f32_e32 v134, v103, v103
	v_max_f32_e32 v135, v71, v71
	v_max_f32_e32 v134, v135, v134
	v_max3_f32 v128, v128, v130, v134
	v_max_f32_e32 v130, v119, v119
	v_max_f32_e32 v134, v87, v87
	v_max_f32_e32 v130, v134, v130
	v_max3_f32 v129, v129, v131, v130
	v_max_f32_e32 v130, v104, v104
	v_max_f32_e32 v131, v72, v72
	v_max_f32_e32 v130, v131, v130
	v_max_f32_e32 v131, v120, v120
	v_max_f32_e32 v134, v88, v88
	v_max_f32_e32 v131, v134, v131
	v_max_f32_e32 v134, v105, v105
	v_max_f32_e32 v135, v73, v73
	v_max_f32_e32 v134, v135, v134
	v_max3_f32 v128, v128, v130, v134
	v_max_f32_e32 v130, v121, v121
	v_max_f32_e32 v134, v89, v89
	v_max_f32_e32 v130, v134, v130
	v_max3_f32 v129, v129, v131, v130
	v_max_f32_e32 v130, v106, v106
	v_max_f32_e32 v131, v74, v74
	v_max_f32_e32 v130, v131, v130
	v_max_f32_e32 v131, v122, v122
	v_max_f32_e32 v134, v90, v90
	v_max_f32_e32 v131, v134, v131
	v_max_f32_e32 v134, v107, v107
	v_max_f32_e32 v135, v75, v75
	v_max_f32_e32 v134, v135, v134
	v_max3_f32 v128, v128, v130, v134
	v_max_f32_e32 v130, v123, v123
	v_max_f32_e32 v134, v91, v91
	v_max_f32_e32 v130, v134, v130
	v_max3_f32 v129, v129, v131, v130
	v_max_f32_e32 v130, v108, v108
	v_max_f32_e32 v131, v76, v76
	v_max_f32_e32 v130, v131, v130
	v_max_f32_e32 v131, v124, v124
	v_max_f32_e32 v134, v92, v92
	v_max_f32_e32 v131, v134, v131
	v_max_f32_e32 v134, v109, v109
	v_max_f32_e32 v135, v77, v77
	v_max_f32_e32 v134, v135, v134
	v_max3_f32 v128, v128, v130, v134
	v_max_f32_e32 v130, v125, v125
	v_max_f32_e32 v134, v93, v93
	v_max_f32_e32 v130, v134, v130
	v_max3_f32 v129, v129, v131, v130
	v_max_f32_e32 v130, v110, v110
	v_max_f32_e32 v131, v78, v78
	v_max_f32_e32 v130, v131, v130
	v_max_f32_e32 v131, v126, v126
	v_max_f32_e32 v134, v94, v94
	v_max_f32_e32 v131, v134, v131
	v_max_f32_e32 v134, v111, v111
	v_max_f32_e32 v135, v79, v79
	v_max_f32_e32 v134, v135, v134
	v_max3_f32 v128, v128, v130, v134
	v_max_f32_e32 v130, v127, v127
	v_max_f32_e32 v134, v95, v95
	v_max_f32_e32 v130, v134, v130
	v_max3_f32 v130, v129, v131, v130
	ds_bpermute_b32 v131, v166, v128
	ds_bpermute_b32 v134, v166, v130
	v_cmp_ngt_f32_e32 vcc, s11, v149
	s_waitcnt lgkmcnt(0)
; DI void attn_pass_da(const bfr* __restrict__ P, int b, int tq_wave, int qcol, int kcol, int vcol, int key0, int nkt, char* smem, f32x16 (&o0)[2], f32x16 (&o1)[2]) {
;     ...
;     float mx0 = s0[0][0], mx1 = s1[0][0];
; #pragma unroll
;     for (int i = 0; i < 16; ++i) { mx0 = fmaxf(mx0, fmaxf(s0[0][i], s0[1][i])); mx1 = fmaxf(mx1, fmaxf(s1[0][i], s1[1][i])); }
;     mx0 = fmaxf(mx0, __shfl_xor(mx0, 32)); mx1 = fmaxf(mx1, __shfl_xor(mx1, 32));
;     const float mn0 = fmaxf(m0, mx0), mn1 = fmaxf(m1, mx1);
;     const float al0 = __builtin_amdgcn_exp2f(m0 - mn0), al1 = __builtin_amdgcn_exp2f(m1 - mn1);
;     m0 = mn0; m1 = mn1;
;     float ps0 = 0.f, ps1 = 0.f;
; #pragma unroll
;     for (int i = 0; i < 16; ++i) {
;       s0[0][i] = __builtin_amdgcn_exp2f(s0[0][i] - mn0); ps0 += s0[0][i];
;       s0[1][i] = __builtin_amdgcn_exp2f(s0[1][i] - mn0); ps0 += s0[1][i];
;       s1[0][i] = __builtin_amdgcn_exp2f(s1[0][i] - mn1); ps1 += s1[0][i];
;       s1[1][i] = __builtin_amdgcn_exp2f(s1[1][i] - mn1); ps1 += s1[1][i];
;     }
;     l0 = l0 * al0 + ps0; l1 = l1 * al1 + ps1;
; #pragma unroll
;     for (int i = 0; i < 16; ++i) { acc0[0][i] *= al0; acc0[1][i] *= al0; acc1[0][i] *= al1; acc1[1][i] *= al1; }
	v_max3_f32 v150, v210, v130, v134
	v_cndmask_b32_e32 v132, 0, v132, vcc
	v_cmp_nlt_f32_e32 vcc, s6, v149
	v_max3_f32 v149, v209, v128, v131
	v_sub_f32_e32 v64, v64, v149
	v_exp_f32_e32 v148, v64
	v_sub_f32_e32 v64, v96, v149
	v_exp_f32_e32 v131, v64
	v_sub_f32_e32 v64, v80, v150
	v_exp_f32_e32 v151, v64
	v_sub_f32_e32 v64, v112, v150
	v_exp_f32_e32 v96, v64
	v_sub_f32_e32 v64, v65, v149
	v_exp_f32_e32 v152, v64
	v_sub_f32_e32 v64, v97, v149
	v_exp_f32_e32 v112, v64
	v_sub_f32_e32 v64, v81, v150
	v_exp_f32_e32 v158, v64
	v_sub_f32_e32 v64, v113, v150
	v_exp_f32_e32 v97, v64
	v_sub_f32_e32 v64, v66, v149
	v_exp_f32_e32 v143, v64
	v_sub_f32_e32 v64, v98, v149
	v_exp_f32_e32 v113, v64
	v_sub_f32_e32 v64, v82, v150
	v_exp_f32_e32 v146, v64
	v_sub_f32_e32 v64, v114, v150
	v_exp_f32_e32 v98, v64
	v_sub_f32_e32 v64, v67, v149
	v_exp_f32_e32 v147, v64
	v_sub_f32_e32 v64, v99, v149
	v_exp_f32_e32 v114, v64
	v_sub_f32_e32 v64, v83, v150
	v_exp_f32_e32 v138, v64
	v_sub_f32_e32 v64, v115, v150
	v_exp_f32_e32 v99, v64
	v_sub_f32_e32 v64, v68, v149
	v_exp_f32_e32 v139, v64
	v_sub_f32_e32 v64, v100, v149
	v_exp_f32_e32 v115, v64
	v_sub_f32_e32 v64, v84, v150
	v_exp_f32_e32 v140, v64
	v_sub_f32_e32 v64, v116, v150
	v_exp_f32_e32 v100, v64
	v_sub_f32_e32 v64, v69, v149
	v_exp_f32_e32 v141, v64
	v_sub_f32_e32 v64, v101, v149
	v_exp_f32_e32 v116, v64
	v_sub_f32_e32 v64, v85, v150
	v_exp_f32_e32 v142, v64
	v_sub_f32_e32 v64, v117, v150
	v_exp_f32_e32 v101, v64
	v_sub_f32_e32 v64, v70, v149
	v_exp_f32_e32 v134, v64
	v_sub_f32_e32 v64, v102, v149
	v_cndmask_b32_e32 v129, v201, v132, vcc
	v_exp_f32_e32 v132, v64
	v_sub_f32_e32 v64, v86, v150
	v_exp_f32_e32 v135, v64
	v_sub_f32_e32 v64, v118, v150
	v_exp_f32_e32 v117, v64
	v_sub_f32_e32 v64, v71, v149
	v_exp_f32_e32 v136, v64
	v_sub_f32_e32 v64, v103, v149
	v_sub_f32_e32 v129, v133, v129
	v_exp_f32_e32 v133, v64
	v_sub_f32_e32 v64, v87, v150
	v_exp_f32_e32 v137, v64
	v_sub_f32_e32 v64, v119, v150
	v_exp_f32_e32 v102, v64
	v_sub_f32_e32 v64, v72, v149
	v_exp_f32_e32 v103, v64
	v_sub_f32_e32 v64, v104, v149
	v_exp_f32_e32 v71, v64
	v_sub_f32_e32 v64, v88, v150
	v_exp_f32_e32 v104, v64
	v_sub_f32_e32 v64, v120, v150
	v_exp_f32_e32 v70, v64
	v_sub_f32_e32 v64, v73, v149
	v_exp_f32_e32 v118, v64
	v_sub_f32_e32 v64, v105, v149
	v_exp_f32_e32 v73, v64
	v_sub_f32_e32 v64, v89, v150
	v_exp_f32_e32 v105, v64
	v_sub_f32_e32 v64, v121, v150
	v_exp_f32_e32 v72, v64
	v_sub_f32_e32 v64, v74, v149
	v_exp_f32_e32 v119, v64
	v_sub_f32_e32 v64, v106, v149
	v_exp_f32_e32 v81, v64
	v_sub_f32_e32 v64, v90, v150
	v_exp_f32_e32 v89, v64
	v_sub_f32_e32 v64, v122, v150
	v_exp_f32_e32 v80, v64
	v_sub_f32_e32 v64, v75, v149
	v_exp_f32_e32 v90, v64
	v_sub_f32_e32 v64, v107, v149
	v_exp_f32_e32 v87, v64
	v_sub_f32_e32 v64, v91, v150
	v_exp_f32_e32 v91, v64
	v_sub_f32_e32 v64, v123, v150
	v_exp_f32_e32 v86, v64
	v_sub_f32_e32 v64, v76, v149
	v_exp_f32_e32 v74, v64
	v_sub_f32_e32 v64, v108, v149
	v_exp_f32_e32 v75, v64
	v_sub_f32_e32 v64, v92, v150
	v_exp_f32_e32 v76, v64
	v_sub_f32_e32 v64, v124, v150
	v_exp_f32_e32 v82, v64
	v_sub_f32_e32 v64, v77, v149
	v_exp_f32_e32 v77, v64
	v_sub_f32_e32 v64, v109, v149
	v_exp_f32_e32 v83, v64
	v_sub_f32_e32 v64, v93, v150
	v_exp_f32_e32 v84, v64
	v_sub_f32_e32 v64, v125, v150
	v_exp_f32_e32 v85, v64
	v_sub_f32_e32 v64, v78, v149
	v_exp_f32_e32 v78, v64
	v_sub_f32_e32 v64, v110, v149
	v_exp_f32_e32 v88, v64
	v_sub_f32_e32 v64, v94, v150
	v_exp_f32_e32 v66, v64
	v_sub_f32_e32 v64, v126, v150
	v_exp_f32_e32 v67, v64
	v_sub_f32_e32 v64, v79, v149
	v_exp_f32_e32 v68, v64
	v_sub_f32_e32 v64, v111, v149
	v_lshl_add_u32 v79, v181, 1, v144
	v_lshl_add_u32 v110, v180, 1, v144
	v_lshl_add_u32 v124, v179, 1, v145
	v_lshl_add_u32 v126, v178, 1, v145
	v_exp_f32_e32 v69, v64
	v_sub_f32_e32 v64, v95, v150
	v_sub_f32_e32 v65, v127, v150
	v_cvt_pk_bf16_f32 v92, v148, v152
	v_cvt_pk_bf16_f32 v93, v143, v147
	v_cvt_pk_bf16_f32 v94, v139, v141
	v_cvt_pk_bf16_f32 v95, v134, v136
	v_cvt_pk_bf16_f32 v106, v151, v158
	v_cvt_pk_bf16_f32 v107, v146, v138
	v_cvt_pk_bf16_f32 v108, v140, v142
	v_cvt_pk_bf16_f32 v109, v135, v137
	ds_read_b64 v[120:121], v79 offset:27648
	ds_read_b64 v[122:123], v110 offset:27648
	ds_read_b64 v[124:125], v124 offset:27648
	ds_read_b64 v[126:127], v126 offset:27648
	v_sub_f32_e32 v128, v209, v149
	v_exp_f32_e32 v130, v128
	v_sub_f32_e32 v128, v210, v150
	v_add_f32_e32 v111, 0, v151
	v_exp_f32_e32 v128, v128
	v_add_f32_e32 v110, 0, v148
	v_add_f32_e32 v111, v96, v111
	v_add_f32_e32 v110, v131, v110
	v_add_f32_e32 v111, v158, v111
	v_add_f32_e32 v110, v152, v110
	v_add_f32_e32 v111, v97, v111
	v_add_f32_e32 v110, v112, v110
	v_add_f32_e32 v111, v146, v111
	v_pk_mul_f32 v[46:47], v[46:47], v[128:129] op_sel_hi:[1,0]
	v_pk_mul_f32 v[44:45], v[44:45], v[128:129] op_sel_hi:[1,0]
	v_pk_mul_f32 v[42:43], v[42:43], v[128:129] op_sel_hi:[1,0]
	v_pk_mul_f32 v[40:41], v[40:41], v[128:129] op_sel_hi:[1,0]
	v_pk_mul_f32 v[38:39], v[38:39], v[128:129] op_sel_hi:[1,0]
	v_pk_mul_f32 v[36:37], v[36:37], v[128:129] op_sel_hi:[1,0]
	v_pk_mul_f32 v[34:35], v[34:35], v[128:129] op_sel_hi:[1,0]
	v_pk_mul_f32 v[32:33], v[32:33], v[128:129] op_sel_hi:[1,0]
	v_pk_mul_f32 v[14:15], v[14:15], v[128:129] op_sel_hi:[1,0]
	v_pk_mul_f32 v[12:13], v[12:13], v[128:129] op_sel_hi:[1,0]
	v_pk_mul_f32 v[10:11], v[10:11], v[128:129] op_sel_hi:[1,0]
	v_pk_mul_f32 v[8:9], v[8:9], v[128:129] op_sel_hi:[1,0]
	v_pk_mul_f32 v[6:7], v[6:7], v[128:129] op_sel_hi:[1,0]
	v_pk_mul_f32 v[4:5], v[4:5], v[128:129] op_sel_hi:[1,0]
	v_pk_mul_f32 v[2:3], v[2:3], v[128:129] op_sel_hi:[1,0]
	v_pk_mul_f32 v[0:1], v[0:1], v[128:129] op_sel_hi:[1,0]
	v_add_f32_e32 v110, v143, v110
	v_add_f32_e32 v111, v98, v111
	s_waitcnt lgkmcnt(2)
; #define MFMA32(a, b, c) __builtin_amdgcn_mfma_f32_32x32x16_bf16((a), (b), (c), 0, 0, 0)
; DI unsigned pack2(float a, float b) { unsigned r; asm volatile("v_cvt_pk_bf16_f32 %0, %1, %2" : "=v"(r) : "v"(a), "v"(b)); return r; }
; DI void attn_pass_da(const bfr* __restrict__ P, int b, int tq_wave, int qcol, int kcol, int vcol, int key0, int nkt, char* smem, f32x16 (&o0)[2], f32x16 (&o1)[2]) {
;     ...
;     l0 = l0 * al0 + ps0; l1 = l1 * al1 + ps1;
; #pragma unroll
;     for (int i = 0; i < 16; ++i) { acc0[0][i] *= al0; acc0[1][i] *= al0; acc1[0][i] *= al1; acc1[1][i] *= al1; }
; #pragma unroll
;     for (int t2 = 0; t2 < 2; ++t2)
; #pragma unroll
;       for (int j = 0; j < 2; ++j) {
;         u32x4 pk0, pk1;
;         pk0.x = pack2(s0[t2][8 * j + 0], s0[t2][8 * j + 1]); pk0.y = pack2(s0[t2][8 * j + 2], s0[t2][8 * j + 3]);
;         pk0.z = pack2(s0[t2][8 * j + 4], s0[t2][8 * j + 5]); pk0.w = pack2(s0[t2][8 * j + 6], s0[t2][8 * j + 7]);
;         pk1.x = pack2(s1[t2][8 * j + 0], s1[t2][8 * j + 1]); pk1.y = pack2(s1[t2][8 * j + 2], s1[t2][8 * j + 3]);
;         pk1.z = pack2(s1[t2][8 * j + 4], s1[t2][8 * j + 5]); pk1.w = pack2(s1[t2][8 * j + 6], s1[t2][8 * j + 7]);
;         const bf16x8 pf0 = __builtin_bit_cast(bf16x8, pk0), pf1 = __builtin_bit_cast(bf16x8, pk1);
; #pragma unroll
;         for (int dt = 0; dt < 2; ++dt) {
;           const int vsw = (((dt * 32 + r) >> 3) & 7) << 3;
;           const bfr* vrow = sV + (dt * 32 + r) * 72;
;           s16x4 lo = *(const s16x4*)(vrow + ((t2 * 32 + 16 * j + 4 * h) ^ vsw));
;           s16x4 hi = *(const s16x4*)(vrow + ((t2 * 32 + 16 * j + 4 * h + 8) ^ vsw));
;           bf16x8 vf = __builtin_shufflevector(lo, hi, 0, 1, 2, 3, 4, 5, 6, 7);
;           acc0[dt] = MFMA32(vf, pf0, acc0[dt]);
;           acc1[dt] = MFMA32(vf, pf1, acc1[dt]);
;         }
;       }
;   }
;   l0 += __shfl_xor(l0, 32); l1 += __shfl_xor(l1, 32);
;   const float i0 = 1.f / l0, i1 = 1.f / l1;
	v_mfma_f32_32x32x16_bf16 v[32:47], v[120:123], v[106:109], v[32:47]
	v_add_f32_e32 v110, v113, v110
	v_add_f32_e32 v110, v147, v110
	v_add_f32_e32 v110, v114, v110
	v_mul_f32_e64 v62, v62, v130
	v_mul_f32_e64 v63, v63, v130
	v_pk_mul_f32 v[60:61], v[60:61], v[130:131] op_sel_hi:[1,0]
	v_pk_mul_f32 v[58:59], v[58:59], v[130:131] op_sel_hi:[1,0]
	v_pk_mul_f32 v[56:57], v[56:57], v[130:131] op_sel_hi:[1,0]
	s_waitcnt lgkmcnt(0)
	v_mfma_f32_32x32x16_bf16 v[0:15], v[124:127], v[106:109], v[0:15]
	v_add_f32_e32 v106, v138, v111
	v_add_f32_e32 v106, v99, v106
	v_add_f32_e32 v106, v140, v106
	v_add_f32_e32 v107, v139, v110
	v_add_f32_e32 v106, v100, v106
	v_add_f32_e32 v107, v115, v107
	v_add_f32_e32 v106, v142, v106
	v_pk_mul_f32 v[54:55], v[54:55], v[130:131] op_sel_hi:[1,0]
	v_pk_mul_f32 v[52:53], v[52:53], v[130:131] op_sel_hi:[1,0]
	v_pk_mul_f32 v[50:51], v[50:51], v[130:131] op_sel_hi:[1,0]
	v_pk_mul_f32 v[48:49], v[48:49], v[130:131] op_sel_hi:[1,0]
	v_pk_mul_f32 v[30:31], v[30:31], v[130:131] op_sel_hi:[1,0]
	v_pk_mul_f32 v[28:29], v[28:29], v[130:131] op_sel_hi:[1,0]
	v_pk_mul_f32 v[26:27], v[26:27], v[130:131] op_sel_hi:[1,0]
	v_pk_mul_f32 v[24:25], v[24:25], v[130:131] op_sel_hi:[1,0]
	v_pk_mul_f32 v[22:23], v[22:23], v[130:131] op_sel_hi:[1,0]
	v_pk_mul_f32 v[20:21], v[20:21], v[130:131] op_sel_hi:[1,0]
	v_pk_mul_f32 v[18:19], v[18:19], v[130:131] op_sel_hi:[1,0]
	v_pk_mul_f32 v[16:17], v[16:17], v[130:131] op_sel_hi:[1,0]
	v_lshl_add_u32 v143, v177, 1, v144
	v_add_f32_e32 v107, v141, v107
	v_add_f32_e32 v111, v101, v106
	v_lshl_add_u32 v106, v175, 1, v145
	v_lshl_add_u32 v108, v174, 1, v145
	v_exp_f32_e32 v64, v64
	v_mfma_f32_32x32x16_bf16 v[48:63], v[120:123], v[92:95], v[48:63]
	v_add_f32_e32 v110, v116, v107
	v_add_f32_e32 v110, v134, v110
	v_add_f32_e32 v110, v132, v110
	v_add_f32_e32 v110, v136, v110
	v_add_f32_e32 v111, v135, v111
	v_add_f32_e32 v111, v117, v111
	v_exp_f32_e32 v65, v65
	v_mfma_f32_32x32x16_bf16 v[16:31], v[124:127], v[92:95], v[16:31]
	v_cvt_pk_bf16_f32 v92, v103, v118
	v_cvt_pk_bf16_f32 v93, v119, v90
	v_cvt_pk_bf16_f32 v94, v74, v77
	v_cvt_pk_bf16_f32 v95, v78, v68
	v_cvt_pk_bf16_f32 v120, v104, v105
	v_cvt_pk_bf16_f32 v121, v89, v91
	v_cvt_pk_bf16_f32 v122, v76, v84
	v_cvt_pk_bf16_f32 v123, v66, v64
	ds_read_b64 v[146:147], v143 offset:27648
	ds_read_b64 v[106:107], v106 offset:27648
	ds_read_b64 v[108:109], v108 offset:27648
	v_lshl_add_u32 v143, v176, 1, v144
	ds_read_b64 v[148:149], v143 offset:27648
	v_add_f32_e32 v124, v133, v110
	s_waitcnt lgkmcnt(0)
	v_mfma_f32_32x32x16_bf16 v[48:63], v[146:149], v[92:95], v[48:63]
	v_add_f32_e32 v125, v137, v111
	v_lshlrev_b32_e32 v152, 1, v154
	v_mfma_f32_32x32x16_bf16 v[16:31], v[106:109], v[92:95], v[16:31]
	v_cvt_pk_bf16_f32 v92, v131, v112
	v_cvt_pk_bf16_f32 v93, v113, v114
	v_cvt_pk_bf16_f32 v94, v115, v116
	v_cvt_pk_bf16_f32 v95, v132, v133
	v_cvt_pk_bf16_f32 v96, v96, v97
	v_cvt_pk_bf16_f32 v97, v98, v99
	v_cvt_pk_bf16_f32 v98, v100, v101
	v_add_f32_e32 v100, v103, v124
	v_add_f32_e32 v100, v71, v100
	v_cvt_pk_bf16_f32 v99, v117, v102
	ds_read_b64 v[110:111], v79 offset:27712
	v_lshl_add_u32 v79, v173, 1, v144
	v_add_f32_e32 v100, v118, v100
	ds_read_b64 v[112:113], v79 offset:27648
	v_add_f32_e32 v79, v102, v125
	v_add_f32_e32 v100, v73, v100
	v_add_f32_e32 v79, v104, v79
	v_add_f32_e32 v104, v119, v100
	v_lshl_add_u32 v100, v172, 1, v145
	v_lshl_add_u32 v102, v171, 1, v145
	ds_read_b64 v[100:101], v100 offset:27648
	ds_read_b64 v[102:103], v102 offset:27648
	v_add_f32_e32 v79, v70, v79
	v_add_f32_e32 v79, v105, v79
	v_add_f32_e32 v79, v72, v79
	v_add_f32_e32 v104, v81, v104
	v_add_f32_e32 v79, v89, v79
	v_add_f32_e32 v79, v80, v79
	v_add_f32_e32 v89, v90, v104
	v_add_f32_e32 v89, v87, v89
	v_add_f32_e32 v79, v91, v79
	v_add_f32_e32 v79, v86, v79
	v_add_f32_e32 v74, v74, v89
	s_waitcnt lgkmcnt(2)
	v_mfma_f32_32x32x16_bf16 v[48:63], v[110:113], v[92:95], v[48:63]
	v_cvt_pk_bf16_f32 v90, v71, v73
	v_cvt_pk_bf16_f32 v91, v81, v87
	v_add_f32_e32 v74, v75, v74
	v_add_f32_e32 v74, v77, v74
	v_add_f32_e32 v74, v83, v74
	v_add_f32_e32 v74, v78, v74
	v_add_f32_e32 v78, v88, v74
	s_waitcnt lgkmcnt(0)
	v_mfma_f32_32x32x16_bf16 v[16:31], v[100:103], v[92:95], v[16:31]
	v_cvt_pk_bf16_f32 v92, v75, v83
	v_add_f32_e32 v75, v76, v79
	v_add_f32_e32 v75, v82, v75
	v_add_f32_e32 v75, v84, v75
	v_add_f32_e32 v79, v85, v75
	v_add_f32_e32 v66, v66, v79
	v_cvt_pk_bf16_f32 v93, v88, v69
	v_mfma_f32_32x32x16_bf16 v[32:47], v[146:149], v[120:123], v[32:47]
	v_cvt_pk_bf16_f32 v70, v70, v72
	v_cvt_pk_bf16_f32 v71, v80, v86
	v_cvt_pk_bf16_f32 v72, v82, v85
	v_cvt_pk_bf16_f32 v73, v67, v65
	v_add_f32_e32 v66, v67, v66
	v_add_f32_e32 v67, v68, v78
	v_add_f32_e32 v67, v69, v67
	v_mfma_f32_32x32x16_bf16 v[0:15], v[106:109], v[120:123], v[0:15]
	v_fmac_f32_e32 v67, v156, v130
	ds_bpermute_b32 v68, v166, v67
	v_lshl_add_u32 v80, v169, 1, v144
	v_lshl_add_u32 v74, v168, 1, v145
	v_lshl_add_u32 v76, v167, 1, v145
	ds_read_b64 v[104:105], v80 offset:27648
	ds_read_b64 v[74:75], v74 offset:27648
	ds_read_b64 v[76:77], v76 offset:27648
	v_lshl_add_u32 v80, v170, 1, v144
	v_add_f32_e32 v64, v64, v66
	ds_read_b64 v[106:107], v80 offset:27648
	v_add_f32_e32 v65, v65, v64
	v_mfma_f32_32x32x16_bf16 v[32:47], v[110:113], v[96:99], v[32:47]
	v_fmac_f32_e32 v65, v157, v128
	s_waitcnt lgkmcnt(4)
	v_add_f32_e32 v66, v67, v68
	ds_bpermute_b32 v67, v166, v65
	v_div_scale_f32 v68, s[6:7], v66, v66, 1.0
	v_rcp_f32_e32 v69, v68
	v_add_f32_e32 v64, v155, v129
	v_mfma_f32_32x32x16_bf16 v[0:15], v[100:103], v[96:99], v[0:15]
	s_waitcnt lgkmcnt(0)
; DI int otid() { int t = threadIdx.x & 255; asm volatile("" : "+v"(t)); return t; }
; DI int oidx(int i) { asm volatile("" : "+s"(i)); return i; }
; DI int vhalf() { int h = __builtin_amdgcn_readfirstlane(threadIdx.x >> 8); asm volatile("" : "+s"(h)); return h; }
; DI void attn_pass_da(const bfr* __restrict__ P, int b, int tq_wave, int qcol, int kcol, int vcol, int key0, int nkt, char* smem, f32x16 (&o0)[2], f32x16 (&o1)[2]) {
;     ...
;   const float i0 = 1.f / l0, i1 = 1.f / l1;
; #pragma unroll
;   for (int i = 0; i < 16; ++i) { o0[0][i] = acc0[0][i] * i0; o0[1][i] = acc0[1][i] * i0; o1[0][i] = acc1[0][i] * i1; o1[1][i] = acc1[1][i] * i1; }
; }
; DI void store_o(bfr* O, int m, int colbase, int h, const f32x16 (&o)[2]) {
; #pragma unroll
;   for (int dt = 0; dt < 2; ++dt)
; #pragma unroll
;     for (int g4 = 0; g4 < 4; ++g4) {
;       int dv = dt * 32 + 8 * g4 + 4 * h;
;       uint2 pk; pk.x = pack2(o[dt][4 * g4], o[dt][4 * g4 + 1]); pk.y = pack2(o[dt][4 * g4 + 2], o[dt][4 * g4 + 3]);
;       *(uint2*)(O + (size_t)m * DM + colbase + dv) = pk;
;     }
; }
; DN void da_item(const Params& p, int l, int b, int hd, int tq0, int key0, int nkt, char* smem) {
;   const bfr* P = (const bfr*)(p.ws + OFF_P);
;   bfr* O = (bfr*)(p.ws + OFF_HO);
;   const int tid = otid(), lane = tid & 63, w = tid >> 6, r = lane & 31, h = lane >> 5;
;   const float* lv = p.in[oidx(22)] + l * 128;
;   float d01 = (lane < 32) ? lv[lane] * lv[32 + lane] : 0.f;
;   float d23 = (lane < 32) ? lv[64 + lane] * lv[96 + lane] : 0.f;
;   d01 = wave_sum(d01); d23 = wave_sum(d23);
;   float lam_init = 0.8f - 0.6f * expf(-0.3f * (float)l);
;   float lam = expf(d01) - expf(d23) + lam_init;
;   f32x16 o0[2], o1[2];
;   int tqw = tq0 + vhalf() * 128 + w * 32;
;   attn_pass_da(P, b, tqw, 1152 + hd * 64, 1408 + hd * 64, 1664 + hd * 64, key0, nkt, smem, o0, o1);
;   float ss = 0.f;
; #pragma unroll
;   for (int dt = 0; dt < 2; ++dt)
; #pragma unroll
;     for (int i = 0; i < 16; ++i) { float v = o0[dt][i] - lam * o1[dt][i]; o0[dt][i] = v; ss += v * v; }
;   ss += __shfl_xor(ss, 32);
;   float rstd = rsqrtf(ss * (1.f / 64.f) + 1e-6f) * (1.f - lam_init);
;   const float* sg = p.in[oidx(23)] + l * 64;
; #pragma unroll
;   for (int dt = 0; dt < 2; ++dt)
; #pragma unroll
;     for (int i = 0; i < 16; ++i) { int dv = dt * 32 + 8 * (i >> 2) + 4 * h + (i & 3); o0[dt][i] = o0[dt][i] * rstd * sg[dv]; }
	v_add_f32_e32 v65, v65, v67
	v_fma_f32 v67, -v68, v69, 1.0
	v_fmac_f32_e32 v69, v67, v69
	v_div_scale_f32 v67, vcc, 1.0, v66, 1.0
	v_mfma_f32_32x32x16_bf16 v[32:47], v[104:107], v[70:73], v[32:47]
	v_mfma_f32_32x32x16_bf16 v[0:15], v[74:77], v[70:73], v[0:15]
	v_mul_f32_e32 v70, v67, v69
	v_fma_f32 v71, -v68, v70, v67
	v_fmac_f32_e32 v70, v71, v69
	v_fma_f32 v67, -v68, v70, v67
	v_div_scale_f32 v68, s[6:7], v65, v65, 1.0
	v_rcp_f32_e32 v71, v68
	v_div_fmas_f32 v67, v67, v69, v70
	v_div_fixup_f32 v66, v67, v66, 1.0
	v_mfma_f32_32x32x16_bf16 v[48:63], v[104:107], v[90:93], v[48:63]
	v_fma_f32 v67, -v68, v71, 1.0
	v_fmac_f32_e32 v71, v67, v71
	v_div_scale_f32 v67, vcc, 1.0, v65, 1.0
	v_mul_f32_e32 v69, v67, v71
	v_fma_f32 v70, -v68, v69, v67
	v_fmac_f32_e32 v69, v70, v71
	v_fma_f32 v67, -v68, v69, v67
	v_div_fmas_f32 v67, v67, v71, v69
	v_div_fixup_f32 v68, v67, v65, 1.0
	v_mul_f32_e32 v65, v0, v68
	v_mul_f32_e32 v0, v33, v68
	v_mul_f32_e32 v67, v1, v68
	v_mul_f32_e32 v1, v34, v68
	v_mul_f32_e32 v0, v64, v0
	v_mul_f32_e32 v32, v32, v68
	v_mul_f32_e32 v69, v2, v68
	v_mul_f32_e32 v2, v35, v68
	v_mul_f32_e32 v33, v37, v68
	v_mul_f32_e32 v37, v41, v68
	v_mul_f32_e32 v41, v45, v68
	v_fma_f32 v45, v49, v66, -v0
	v_mul_f32_e32 v0, v64, v1
	v_mul_f32_e32 v70, v3, v68
	v_mul_f32_e32 v3, v36, v68
	v_mul_f32_e32 v35, v39, v68
	v_mul_f32_e32 v39, v43, v68
	v_mul_f32_e32 v43, v47, v68
	v_mul_f32_e32 v32, v64, v32
	v_fma_f32 v47, v50, v66, -v0
	v_mul_f32_e32 v0, v64, v2
	v_mul_f32_e32 v36, v40, v68
	v_mul_f32_e32 v40, v44, v68
	v_fma_f32 v44, v48, v66, -v32
	v_fma_f32 v48, v51, v66, -v0
	v_mul_f32_e32 v0, v64, v3
	v_mul_f32_e32 v34, v38, v68
	v_fma_f32 v49, v52, v66, -v0
	v_mul_f32_e32 v0, v64, v33
	s_mov_b32 s6, 23
	v_fma_f32 v50, v53, v66, -v0
	v_mul_f32_e32 v0, v64, v34
	s_ashr_i32 s7, s6, 31
	v_fma_f32 v51, v54, v66, -v0
	v_mul_f32_e32 v0, v64, v35
	s_lshl_b64 s[6:7], s[6:7], 3
	v_fma_f32 v52, v55, v66, -v0
	v_mul_f32_e32 v0, v64, v36
	s_add_u32 s6, s0, s6
	v_mul_f32_e32 v38, v42, v68
	v_fma_f32 v53, v56, v66, -v0
	v_mul_f32_e32 v0, v64, v37
	s_addc_u32 s7, s1, s7
	v_fma_f32 v54, v57, v66, -v0
	v_mul_f32_e32 v0, v64, v38
	s_load_dwordx2 s[6:7], s[6:7], 0x0
	v_mul_f32_e32 v42, v46, v68
	v_mul_f32_e32 v46, v45, v45
	v_fma_f32 v55, v58, v66, -v0
	v_mul_f32_e32 v0, v64, v39
	v_fmac_f32_e32 v46, v44, v44
	v_fma_f32 v56, v59, v66, -v0
	v_mul_f32_e32 v0, v64, v40
	v_fmac_f32_e32 v46, v47, v47
	v_fma_f32 v57, v60, v66, -v0
	v_mul_f32_e32 v0, v64, v41
	v_fmac_f32_e32 v46, v48, v48
	v_fma_f32 v58, v61, v66, -v0
	s_lshl_b64 s[8:9], s[8:9], 2
	v_lshrrev_b32_e32 v0, 3, v164
	v_fmac_f32_e32 v46, v49, v49
	s_waitcnt lgkmcnt(0)
	s_add_u32 s6, s6, s8
	v_and_b32_e32 v59, 4, v0
	v_fmac_f32_e32 v46, v50, v50
	s_addc_u32 s7, s7, s9
	v_lshlrev_b32_e32 v60, 2, v59
	v_mfma_f32_32x32x16_bf16 v[16:31], v[74:77], v[90:93], v[16:31]
	v_fmac_f32_e32 v46, v51, v51
	global_load_dwordx4 v[0:3], v60, s[6:7]
	v_fmac_f32_e32 v46, v52, v52
	v_fmac_f32_e32 v46, v53, v53
	v_mul_f32_e32 v32, v64, v42
	v_fmac_f32_e32 v46, v54, v54
	v_fma_f32 v61, v62, v66, -v32
	v_mul_f32_e32 v32, v64, v43
	v_fmac_f32_e32 v46, v55, v55
	v_fma_f32 v62, v63, v66, -v32
	global_load_dwordx4 v[32:35], v60, s[6:7] offset:32
	v_fmac_f32_e32 v46, v56, v56
	v_fmac_f32_e32 v46, v57, v57
	v_fmac_f32_e32 v46, v58, v58
	v_mul_f32_e32 v36, v64, v65
	v_fmac_f32_e32 v46, v61, v61
	v_fma_f32 v63, v16, v66, -v36
	v_mul_f32_e32 v16, v64, v67
	global_load_dwordx4 v[36:39], v60, s[6:7] offset:64
	v_mul_f32_e32 v4, v4, v68
	v_fmac_f32_e32 v46, v62, v62
	v_fma_f32 v65, v17, v66, -v16
	v_mul_f32_e32 v16, v64, v69
	v_mul_f32_e32 v5, v5, v68
	v_fmac_f32_e32 v46, v63, v63
	v_fma_f32 v67, v18, v66, -v16
	v_mul_f32_e32 v16, v64, v70
	v_mul_f32_e32 v4, v64, v4
	v_fmac_f32_e32 v46, v65, v65
	v_fma_f32 v69, v19, v66, -v16
	v_fma_f32 v70, v20, v66, -v4
	v_mul_f32_e32 v4, v64, v5
	v_fmac_f32_e32 v46, v67, v67
	global_load_dwordx4 v[16:19], v60, s[6:7] offset:96
	v_fma_f32 v71, v21, v66, -v4
	v_pk_mul_f32 v[4:5], v[6:7], v[68:69] op_sel_hi:[1,0]
	v_fmac_f32_e32 v46, v69, v69
	v_pk_mul_f32 v[4:5], v[64:65], v[4:5] op_sel_hi:[0,1]
	v_fmac_f32_e32 v46, v70, v70
	v_pk_fma_f32 v[40:41], v[22:23], v[66:67], v[4:5] op_sel_hi:[1,0,1] neg_lo:[0,0,1] neg_hi:[0,0,1]
	v_pk_mul_f32 v[8:9], v[8:9], v[68:69] op_sel_hi:[1,0]
	v_fmac_f32_e32 v46, v71, v71
	v_pk_mul_f32 v[20:21], v[40:41], v[40:41]
	v_pk_mul_f32 v[8:9], v[64:65], v[8:9] op_sel_hi:[0,1]
	global_load_dwordx4 v[4:7], v60, s[6:7] offset:128
	v_add_f32_e32 v20, v20, v46
	v_pk_fma_f32 v[24:25], v[24:25], v[66:67], v[8:9] op_sel_hi:[1,0,1] neg_lo:[0,0,1] neg_hi:[0,0,1]
	v_add_f32_e32 v20, v21, v20
	v_pk_mul_f32 v[8:9], v[24:25], v[24:25]
	v_pk_mul_f32 v[12:13], v[12:13], v[68:69] op_sel_hi:[1,0]
	v_add_f32_e32 v8, v8, v20
	v_add_f32_e32 v42, v9, v8
	v_pk_mul_f32 v[8:9], v[10:11], v[68:69] op_sel_hi:[1,0]
	global_load_dwordx4 v[20:23], v60, s[6:7] offset:160
	v_pk_mul_f32 v[8:9], v[64:65], v[8:9] op_sel_hi:[0,1]
	v_pk_fma_f32 v[26:27], v[26:27], v[66:67], v[8:9] op_sel_hi:[1,0,1] neg_lo:[0,0,1] neg_hi:[0,0,1]
	v_pk_mul_f32 v[12:13], v[64:65], v[12:13] op_sel_hi:[0,1]
	v_pk_mul_f32 v[8:9], v[26:27], v[26:27]
	v_pk_fma_f32 v[28:29], v[28:29], v[66:67], v[12:13] op_sel_hi:[1,0,1] neg_lo:[0,0,1] neg_hi:[0,0,1]
	v_add_f32_e32 v8, v8, v42
	v_add_f32_e32 v42, v9, v8
	global_load_dwordx4 v[8:11], v60, s[6:7] offset:192
	v_pk_mul_f32 v[12:13], v[28:29], v[28:29]
	s_load_dwordx4 s[8:11], s[0:1], 0x100
	v_add_f32_e32 v12, v12, v42
	v_add_f32_e32 v46, v13, v12
	v_pk_mul_f32 v[42:43], v[14:15], v[68:69] op_sel_hi:[1,0]
	global_load_dwordx4 v[12:15], v60, s[6:7] offset:224
	v_pk_mul_f32 v[42:43], v[64:65], v[42:43] op_sel_hi:[0,1]
	v_pk_fma_f32 v[30:31], v[30:31], v[66:67], v[42:43] op_sel_hi:[1,0,1] neg_lo:[0,0,1] neg_hi:[0,0,1]
	s_mov_b64 s[6:7], 0x2b7c300
	v_pk_mul_f32 v[42:43], v[30:31], v[30:31]
	s_nop 0
	v_add_f32_e32 v42, v42, v46
	v_add_f32_e32 v42, v43, v42
	ds_bpermute_b32 v43, v166, v42
	s_waitcnt lgkmcnt(0)
; DI int oidx(int i) { asm volatile("" : "+s"(i)); return i; }
; DI unsigned pack2(float a, float b) { unsigned r; asm volatile("v_cvt_pk_bf16_f32 %0, %1, %2" : "=v"(r) : "v"(a), "v"(b)); return r; }
; DI void store_o(bfr* O, int m, int colbase, int h, const f32x16 (&o)[2]) {
; #pragma unroll
;   for (int dt = 0; dt < 2; ++dt)
; #pragma unroll
;     for (int g4 = 0; g4 < 4; ++g4) {
;       int dv = dt * 32 + 8 * g4 + 4 * h;
;       uint2 pk; pk.x = pack2(o[dt][4 * g4], o[dt][4 * g4 + 1]); pk.y = pack2(o[dt][4 * g4 + 2], o[dt][4 * g4 + 3]);
;       *(uint2*)(O + (size_t)m * DM + colbase + dv) = pk;
;     }
; }
; DN void da_item(const Params& p, int l, int b, int hd, int tq0, int key0, int nkt, char* smem) {
;     ...
;   ss += __shfl_xor(ss, 32);
;   float rstd = rsqrtf(ss * (1.f / 64.f) + 1e-6f) * (1.f - lam_init);
;   const float* sg = p.in[oidx(23)] + l * 64;
; #pragma unroll
;   for (int dt = 0; dt < 2; ++dt)
; #pragma unroll
;     for (int i = 0; i < 16; ++i) { int dv = dt * 32 + 8 * (i >> 2) + 4 * h + (i & 3); o0[dt][i] = o0[dt][i] * rstd * sg[dv]; }
;   store_o(O, b * TT + tqw + r, 256 + hd * 64, h, o0);
	v_add_f32_e32 v42, v42, v43
	v_fmamk_f32 v42, v42, 0x3c800000, v186
	v_cmp_gt_f32_e32 vcc, s33, v42
	v_mul_f32_e32 v43, 0x4b800000, v42
	s_nop 0
	v_cndmask_b32_e32 v42, v42, v43, vcc
	v_rsq_f32_e32 v42, v42
	s_nop 0
	v_mul_f32_e32 v43, 0x45800000, v42
	v_cndmask_b32_e32 v42, v42, v43, vcc
	v_mul_f32_e32 v42, v162, v42
	v_mul_f32_e32 v43, v44, v42
	s_waitcnt vmcnt(7)
	v_mul_f32_e32 v43, v0, v43
	v_mul_f32_e32 v0, v45, v42
	v_mul_f32_e32 v44, v1, v0
	v_mul_f32_e32 v0, v47, v42
	v_mul_f32_e32 v45, v2, v0
	v_mul_f32_e32 v0, v48, v42
	v_mul_f32_e32 v3, v3, v0
	v_mul_f32_e32 v0, v49, v42
	s_waitcnt vmcnt(6)
	v_mul_f32_e32 v32, v32, v0
	v_mul_f32_e32 v0, v50, v42
	v_mul_f32_e32 v33, v33, v0
	v_mul_f32_e32 v0, v51, v42
	v_mul_f32_e32 v34, v34, v0
	v_mul_f32_e32 v0, v52, v42
	v_mul_f32_e32 v35, v35, v0
	v_mul_f32_e32 v0, v53, v42
	s_waitcnt vmcnt(5)
	v_mul_f32_e32 v36, v36, v0
	v_mul_f32_e32 v0, v54, v42
	v_mul_f32_e32 v37, v37, v0
	v_mul_f32_e32 v0, v55, v42
	v_mul_f32_e32 v38, v38, v0
	v_mul_f32_e32 v0, v56, v42
	v_mul_f32_e32 v39, v39, v0
	v_mul_f32_e32 v0, v57, v42
	s_waitcnt vmcnt(4)
	v_mul_f32_e32 v16, v16, v0
	v_mul_f32_e32 v0, v58, v42
	v_mul_f32_e32 v17, v17, v0
	v_mul_f32_e32 v0, v61, v42
	v_mul_f32_e32 v18, v18, v0
	v_mul_f32_e32 v0, v62, v42
	v_mul_f32_e32 v19, v19, v0
	v_mul_f32_e32 v0, v63, v42
	s_waitcnt vmcnt(3)
	v_mul_f32_e32 v46, v4, v0
	v_mul_f32_e32 v0, v65, v42
	v_mul_f32_e32 v47, v5, v0
	v_mul_f32_e32 v0, v67, v42
	v_mul_f32_e32 v6, v6, v0
	v_mul_f32_e32 v0, v69, v42
	v_mul_f32_e32 v7, v7, v0
	v_mul_f32_e32 v0, v70, v42
	s_waitcnt vmcnt(2)
	v_mul_f32_e32 v20, v20, v0
	v_mul_f32_e32 v0, v71, v42
	v_mul_f32_e32 v21, v21, v0
	v_mul_f32_e32 v0, v40, v42
	v_mul_f32_e32 v22, v22, v0
	v_mul_f32_e32 v0, v41, v42
	v_mul_f32_e32 v23, v23, v0
	v_mul_f32_e32 v0, v24, v42
	s_waitcnt vmcnt(1)
	v_mul_f32_e32 v8, v8, v0
	v_mul_f32_e32 v0, v25, v42
	v_mul_f32_e32 v9, v9, v0
	v_mul_f32_e32 v0, v26, v42
	v_mul_f32_e32 v10, v10, v0
	v_mul_f32_e32 v0, v27, v42
	v_mul_f32_e32 v11, v11, v0
	v_mul_f32_e32 v0, v28, v42
	s_waitcnt vmcnt(0)
	v_mul_f32_e32 v12, v12, v0
	v_mul_f32_e32 v0, v29, v42
	v_mul_f32_e32 v13, v13, v0
	v_mul_f32_e32 v0, v30, v42
	v_mul_f32_e32 v14, v14, v0
	v_mul_f32_e32 v0, v31, v42
	v_mul_f32_e32 v15, v15, v0
	v_and_or_b32 v0, v164, 31, v165
	v_ashrrev_i32_e32 v1, 31, v0
	v_lshlrev_b64 v[0:1], 11, v[0:1]
	v_lshl_add_u64 v[0:1], s[10:11], 0, v[0:1]
	v_lshl_add_u64 v[0:1], v[0:1], 0, v[152:153]
	v_lshlrev_b32_e32 v152, 1, v59
	v_lshl_add_u64 v[0:1], v[0:1], 0, v[152:153]
	v_lshl_add_u64 v[4:5], v[0:1], 0, s[6:7]
	s_mov_b32 s6, 0x2b7c000
	v_add_co_u32_e32 v0, vcc, s6, v0
	v_cvt_pk_bf16_f32 v2, v43, v44
	v_cvt_pk_bf16_f32 v3, v45, v3
	s_nop 1
	v_addc_co_u32_e32 v1, vcc, 0, v1, vcc
	global_store_dwordx2 v[0:1], v[2:3], off offset:768
	v_cvt_pk_bf16_f32 v0, v32, v33
	v_cvt_pk_bf16_f32 v1, v34, v35
	global_store_dwordx2 v[4:5], v[0:1], off offset:16
	v_cvt_pk_bf16_f32 v0, v36, v37
	v_cvt_pk_bf16_f32 v1, v38, v39
	global_store_dwordx2 v[4:5], v[0:1], off offset:32
	v_cvt_pk_bf16_f32 v0, v16, v17
	v_cvt_pk_bf16_f32 v1, v18, v19
	global_store_dwordx2 v[4:5], v[0:1], off offset:48
	v_cvt_pk_bf16_f32 v0, v46, v47
	v_cvt_pk_bf16_f32 v1, v6, v7
	global_store_dwordx2 v[4:5], v[0:1], off offset:64
	v_cvt_pk_bf16_f32 v0, v20, v21
	v_cvt_pk_bf16_f32 v1, v22, v23
	global_store_dwordx2 v[4:5], v[0:1], off offset:80
	v_cvt_pk_bf16_f32 v0, v8, v9
	v_cvt_pk_bf16_f32 v1, v10, v11
	global_store_dwordx2 v[4:5], v[0:1], off offset:96
	v_cvt_pk_bf16_f32 v0, v12, v13
	v_cvt_pk_bf16_f32 v1, v14, v15
	global_store_dwordx2 v[4:5], v[0:1], off offset:112
